# static priority: waves 4-7 at s_setprio 1 for the whole kernel, per-segment setprio flips removed from the GEMM K-loops
# baseline (speedup 1.0000x reference)
_Z10fwd_kernel6Params:
	s_load_dwordx2 s[16:17], s[0:1], 0xd0
	v_and_b32_e32 v220, 0x3ff, v0
	s_add_u32 s4, s0, 0xd0
	v_mov_b32_e32 v2, v220
	s_addc_u32 s5, s1, 0
	s_nop 0
	v_readfirstlane_b32 s18, v2
	s_cmpk_lt_u32 s18, 0x100
	s_cbranch_scc1 .Lprio_skip
	s_setprio 1
.Lprio_skip:
	v_cmp_gt_i32_e32 vcc, 26, v2
	s_and_saveexec_b64 s[6:7], vcc
	s_cbranch_execz .LBB0_2
	v_ashrrev_i32_e32 v3, 31, v2
	v_lshl_add_u64 v[4:5], v[2:3], 3, s[0:1]
	global_load_dwordx2 v[4:5], v[4:5], off
	v_lshl_add_u32 v1, v2, 3, 0
	v_add_u32_e32 v1, 0x20000, v1
	s_waitcnt vmcnt(0)
	ds_write_b64 v1, v[4:5]

.LBB0_255:
	s_ashr_i32 s15, s14, 31
	s_lshl_b64 s[20:21], s[14:15], 19
	s_add_u32 s42, s31, s20
	s_addc_u32 s43, s34, s21
	s_and_b64 s[20:21], s[4:5], exec
	s_cselect_b32 s15, s43, s53
	s_cselect_b32 s20, s42, s52
	s_ashr_i32 s13, s12, 31
	s_lshl_b64 s[50:51], s[12:13], 19
	s_add_u32 s50, s35, s50
	s_addc_u32 s51, s36, s51
	s_and_b64 s[58:59], s[4:5], exec
	s_cselect_b32 s13, s51, s57
	s_cselect_b32 s21, s50, s56
	s_add_u32 s52, s52, 0x40080
	s_addc_u32 s53, s53, 0
	s_add_u32 s73, s56, 0x100
	s_addc_u32 s75, s57, 0
	s_mov_b32 s82, -2
	s_add_u32 s0, s52, 0xfffc0080
	s_addc_u32 s56, s53, -1
	s_add_i32 s83, 0, 0x10000
	s_cmp_eq_u32 s82, 12
	s_cselect_b32 s59, s15, s56
	s_cselect_b32 s58, s20, s0
	s_cselect_b32 s57, s13, s75
	s_cselect_b32 s56, s21, s73
	s_add_i32 s0, 0, 0x14000
	v_add_u32_e32 v94, s83, v171
	v_add_u32_e32 v155, s0, v171
	ds_read_b128 v[74:77], v94
	ds_read_b128 v[78:81], v94 offset:1024
	ds_read_b128 v[90:93], v94 offset:2048
	ds_read_b128 v[94:97], v94 offset:3072
	ds_read_b128 v[180:183], v155
	ds_read_b128 v[184:187], v155 offset:1024
	ds_read_b128 v[188:191], v155 offset:2048
	ds_read_b128 v[192:195], v155 offset:3072
	v_lshl_add_u64 v[168:169], s[52:53], 0, v[164:165]
	s_add_i32 m0, s61, 0xc000
	ds_read_b128 v[196:199], v177
	ds_read_b128 v[200:203], v177 offset:1024
	ds_read_b128 v[204:207], v177 offset:2048
	ds_read_b128 v[208:211], v177 offset:3072
	ds_read_b128 v[212:215], v177 offset:4096
	ds_read_b128 v[216:219], v177 offset:5120
	ds_read_b128 v[230:233], v177 offset:6144
	ds_read_b128 v[238:241], v177 offset:7168
	global_load_lds_dwordx4 v[168:169], off
	v_lshl_add_u64 v[168:169], s[52:53], 0, v[166:167]
	s_add_i32 m0, s61, 0xe000
	s_nop 0
	global_load_lds_dwordx4 v[168:169], off
	s_waitcnt vmcnt(8)
	s_waitcnt lgkmcnt(0)
	s_barrier
	s_waitcnt lgkmcnt(0)
	v_mfma_f32_16x16x32_bf16 v[142:145], v[74:77], v[196:199], 0
	v_mfma_f32_16x16x32_bf16 v[134:137], v[90:93], v[196:199], 0
	v_mfma_f32_16x16x32_bf16 v[126:129], v[74:77], v[204:207], 0
	v_mfma_f32_16x16x32_bf16 v[118:121], v[90:93], v[204:207], 0
	v_mfma_f32_16x16x32_bf16 v[110:113], v[74:77], v[212:215], 0
	v_mfma_f32_16x16x32_bf16 v[102:105], v[90:93], v[212:215], 0
	v_mfma_f32_16x16x32_bf16 v[86:89], v[74:77], v[230:233], 0
	v_mfma_f32_16x16x32_bf16 v[70:73], v[90:93], v[230:233], 0
	v_mfma_f32_16x16x32_bf16 v[142:145], v[78:81], v[200:203], v[142:145]
	v_mfma_f32_16x16x32_bf16 v[134:137], v[94:97], v[200:203], v[134:137]
	v_mfma_f32_16x16x32_bf16 v[126:129], v[78:81], v[208:211], v[126:129]
	v_mfma_f32_16x16x32_bf16 v[118:121], v[94:97], v[208:211], v[118:121]
	v_mfma_f32_16x16x32_bf16 v[110:113], v[78:81], v[216:219], v[110:113]
	v_mfma_f32_16x16x32_bf16 v[102:105], v[94:97], v[216:219], v[102:105]
	v_mfma_f32_16x16x32_bf16 v[86:89], v[78:81], v[238:241], v[86:89]
	v_mfma_f32_16x16x32_bf16 v[70:73], v[94:97], v[238:241], v[70:73]
	v_mfma_f32_16x16x32_bf16 v[138:141], v[180:183], v[196:199], 0
	v_mfma_f32_16x16x32_bf16 v[130:133], v[188:191], v[196:199], 0
	v_mfma_f32_16x16x32_bf16 v[122:125], v[180:183], v[204:207], 0
	v_mfma_f32_16x16x32_bf16 v[114:117], v[188:191], v[204:207], 0
	v_mfma_f32_16x16x32_bf16 v[106:109], v[180:183], v[212:215], 0
	v_mfma_f32_16x16x32_bf16 v[98:101], v[188:191], v[212:215], 0
	v_mfma_f32_16x16x32_bf16 v[82:85], v[180:183], v[230:233], 0
	v_mfma_f32_16x16x32_bf16 v[66:69], v[188:191], v[230:233], 0
	v_mfma_f32_16x16x32_bf16 v[138:141], v[184:187], v[200:203], v[138:141]
	v_mfma_f32_16x16x32_bf16 v[130:133], v[192:195], v[200:203], v[130:133]
	v_mfma_f32_16x16x32_bf16 v[122:125], v[184:187], v[208:211], v[122:125]
	v_mfma_f32_16x16x32_bf16 v[114:117], v[192:195], v[208:211], v[114:117]
	v_mfma_f32_16x16x32_bf16 v[106:109], v[184:187], v[216:219], v[106:109]
	v_mfma_f32_16x16x32_bf16 v[98:101], v[192:195], v[216:219], v[98:101]
	v_mfma_f32_16x16x32_bf16 v[82:85], v[184:187], v[238:241], v[82:85]
	v_mfma_f32_16x16x32_bf16 v[66:69], v[192:195], v[238:241], v[66:69]
	s_barrier
	s_add_i32 s83, s83, s37
	v_lshl_add_u64 v[168:169], s[56:57], 0, v[150:151]
	s_mov_b32 m0, s83
	ds_read_b128 v[196:199], v177 offset:16384
	ds_read_b128 v[200:203], v177 offset:17408
	ds_read_b128 v[204:207], v177 offset:18432
	ds_read_b128 v[208:211], v177 offset:19456
	ds_read_b128 v[212:215], v177 offset:20480
	ds_read_b128 v[216:219], v177 offset:21504
	ds_read_b128 v[230:233], v177 offset:22528
	ds_read_b128 v[238:241], v177 offset:23552
	global_load_lds_dwordx4 v[168:169], off
	s_add_i32 m0, s83, 0x2000
	s_add_u32 s84, s56, 0x40000
	v_lshl_add_u64 v[242:243], s[56:57], 0, v[146:147]
	s_addc_u32 s85, s57, 0
	s_add_i32 s0, s0, s37
	global_load_lds_dwordx4 v[242:243], off
	v_lshl_add_u64 v[244:245], s[84:85], 0, v[150:151]
	s_mov_b32 m0, s0
	v_lshl_add_u64 v[246:247], s[58:59], 0, v[148:149]
	global_load_lds_dwordx4 v[244:245], off
	v_lshl_add_u64 v[244:245], s[84:85], 0, v[146:147]
	s_add_i32 m0, s0, 0x2000
	s_nop 0
	global_load_lds_dwordx4 v[244:245], off
	v_lshl_add_u64 v[244:245], s[58:59], 0, v[152:153]
	s_mov_b32 m0, s61
	s_nop 0
	global_load_lds_dwordx4 v[244:245], off
	s_mov_b32 m0, s64
	s_nop 0
	global_load_lds_dwordx4 v[246:247], off
	s_waitcnt vmcnt(8)
	s_waitcnt lgkmcnt(0)
	s_barrier
	s_waitcnt lgkmcnt(0)
	v_mfma_f32_16x16x32_bf16 v[62:65], v[74:77], v[196:199], 0
	v_mfma_f32_16x16x32_bf16 v[54:57], v[90:93], v[196:199], 0
	v_mfma_f32_16x16x32_bf16 v[46:49], v[74:77], v[204:207], 0
	v_mfma_f32_16x16x32_bf16 v[38:41], v[90:93], v[204:207], 0
	v_mfma_f32_16x16x32_bf16 v[30:33], v[74:77], v[212:215], 0
	v_mfma_f32_16x16x32_bf16 v[22:25], v[90:93], v[212:215], 0
	v_mfma_f32_16x16x32_bf16 v[14:17], v[74:77], v[230:233], 0
	v_mfma_f32_16x16x32_bf16 v[6:9], v[90:93], v[230:233], 0
	v_mfma_f32_16x16x32_bf16 v[62:65], v[78:81], v[200:203], v[62:65]
	v_mfma_f32_16x16x32_bf16 v[54:57], v[94:97], v[200:203], v[54:57]
	v_mfma_f32_16x16x32_bf16 v[46:49], v[78:81], v[208:211], v[46:49]
	v_mfma_f32_16x16x32_bf16 v[38:41], v[94:97], v[208:211], v[38:41]
	v_mfma_f32_16x16x32_bf16 v[30:33], v[78:81], v[216:219], v[30:33]
	v_mfma_f32_16x16x32_bf16 v[22:25], v[94:97], v[216:219], v[22:25]
	v_mfma_f32_16x16x32_bf16 v[14:17], v[78:81], v[238:241], v[14:17]
	v_mfma_f32_16x16x32_bf16 v[6:9], v[94:97], v[238:241], v[6:9]
	v_mfma_f32_16x16x32_bf16 v[58:61], v[180:183], v[196:199], 0
	v_mfma_f32_16x16x32_bf16 v[50:53], v[188:191], v[196:199], 0
	v_mfma_f32_16x16x32_bf16 v[42:45], v[180:183], v[204:207], 0
	v_mfma_f32_16x16x32_bf16 v[34:37], v[188:191], v[204:207], 0
	v_mfma_f32_16x16x32_bf16 v[26:29], v[180:183], v[212:215], 0
	v_mfma_f32_16x16x32_bf16 v[18:21], v[188:191], v[212:215], 0
	v_mfma_f32_16x16x32_bf16 v[10:13], v[180:183], v[230:233], 0
	v_mfma_f32_16x16x32_bf16 v[2:5], v[188:191], v[230:233], 0
	v_mfma_f32_16x16x32_bf16 v[58:61], v[184:187], v[200:203], v[58:61]
	v_mfma_f32_16x16x32_bf16 v[50:53], v[192:195], v[200:203], v[50:53]
	v_mfma_f32_16x16x32_bf16 v[42:45], v[184:187], v[208:211], v[42:45]
	v_mfma_f32_16x16x32_bf16 v[34:37], v[192:195], v[208:211], v[34:37]
	v_mfma_f32_16x16x32_bf16 v[26:29], v[184:187], v[216:219], v[26:29]
	v_mfma_f32_16x16x32_bf16 v[18:21], v[192:195], v[216:219], v[18:21]
	v_mfma_f32_16x16x32_bf16 v[10:13], v[184:187], v[238:241], v[10:13]
	v_mfma_f32_16x16x32_bf16 v[2:5], v[192:195], v[238:241], v[2:5]
	s_barrier
	s_add_i32 s0, 0, 0x18000
	s_add_i32 s83, 0, 0x1c000
	v_add_u32_e32 v94, s0, v171
	v_add_u32_e32 v155, s83, v171
	ds_read_b128 v[74:77], v94
	ds_read_b128 v[78:81], v94 offset:1024
	ds_read_b128 v[90:93], v94 offset:2048
	ds_read_b128 v[94:97], v94 offset:3072
	ds_read_b128 v[180:183], v155
	ds_read_b128 v[184:187], v155 offset:1024
	ds_read_b128 v[188:191], v155 offset:2048
	ds_read_b128 v[192:195], v155 offset:3072
	s_add_u32 s58, s58, 0x40000
	s_addc_u32 s59, s59, 0
	s_mov_b32 m0, s65
	v_lshl_add_u64 v[248:249], s[58:59], 0, v[152:153]
	ds_read_b128 v[196:199], v177 offset:32768
	ds_read_b128 v[200:203], v177 offset:33792
	ds_read_b128 v[204:207], v177 offset:34816
	ds_read_b128 v[208:211], v177 offset:35840
	ds_read_b128 v[212:215], v177 offset:36864
	ds_read_b128 v[216:219], v177 offset:37888
	ds_read_b128 v[230:233], v177 offset:38912
	ds_read_b128 v[238:241], v177 offset:39936
	global_load_lds_dwordx4 v[248:249], off
	v_lshl_add_u64 v[248:249], s[58:59], 0, v[148:149]
	s_mov_b32 m0, s66
	s_nop 0
	global_load_lds_dwordx4 v[248:249], off
	s_waitcnt vmcnt(8)
	s_waitcnt lgkmcnt(0)
	s_barrier
	s_waitcnt lgkmcnt(0)
	v_mfma_f32_16x16x32_bf16 v[142:145], v[74:77], v[196:199], v[142:145]
	v_mfma_f32_16x16x32_bf16 v[134:137], v[90:93], v[196:199], v[134:137]
	v_mfma_f32_16x16x32_bf16 v[126:129], v[74:77], v[204:207], v[126:129]
	v_mfma_f32_16x16x32_bf16 v[118:121], v[90:93], v[204:207], v[118:121]
	v_mfma_f32_16x16x32_bf16 v[110:113], v[74:77], v[212:215], v[110:113]
	v_mfma_f32_16x16x32_bf16 v[102:105], v[90:93], v[212:215], v[102:105]
	v_mfma_f32_16x16x32_bf16 v[86:89], v[74:77], v[230:233], v[86:89]
	v_mfma_f32_16x16x32_bf16 v[70:73], v[90:93], v[230:233], v[70:73]
	v_mfma_f32_16x16x32_bf16 v[142:145], v[78:81], v[200:203], v[142:145]
	v_mfma_f32_16x16x32_bf16 v[134:137], v[94:97], v[200:203], v[134:137]
	v_mfma_f32_16x16x32_bf16 v[126:129], v[78:81], v[208:211], v[126:129]
	v_mfma_f32_16x16x32_bf16 v[118:121], v[94:97], v[208:211], v[118:121]
	v_mfma_f32_16x16x32_bf16 v[110:113], v[78:81], v[216:219], v[110:113]
	v_mfma_f32_16x16x32_bf16 v[102:105], v[94:97], v[216:219], v[102:105]
	v_mfma_f32_16x16x32_bf16 v[86:89], v[78:81], v[238:241], v[86:89]
	v_mfma_f32_16x16x32_bf16 v[70:73], v[94:97], v[238:241], v[70:73]
	v_mfma_f32_16x16x32_bf16 v[138:141], v[180:183], v[196:199], v[138:141]
	v_mfma_f32_16x16x32_bf16 v[130:133], v[188:191], v[196:199], v[130:133]
	v_mfma_f32_16x16x32_bf16 v[122:125], v[180:183], v[204:207], v[122:125]
	v_mfma_f32_16x16x32_bf16 v[114:117], v[188:191], v[204:207], v[114:117]
	v_mfma_f32_16x16x32_bf16 v[106:109], v[180:183], v[212:215], v[106:109]
	v_mfma_f32_16x16x32_bf16 v[98:101], v[188:191], v[212:215], v[98:101]
	v_mfma_f32_16x16x32_bf16 v[82:85], v[180:183], v[230:233], v[82:85]
	v_mfma_f32_16x16x32_bf16 v[66:69], v[188:191], v[230:233], v[66:69]
	v_mfma_f32_16x16x32_bf16 v[138:141], v[184:187], v[200:203], v[138:141]
	v_mfma_f32_16x16x32_bf16 v[130:133], v[192:195], v[200:203], v[130:133]
	v_mfma_f32_16x16x32_bf16 v[122:125], v[184:187], v[208:211], v[122:125]
	v_mfma_f32_16x16x32_bf16 v[114:117], v[192:195], v[208:211], v[114:117]
	v_mfma_f32_16x16x32_bf16 v[106:109], v[184:187], v[216:219], v[106:109]
	v_mfma_f32_16x16x32_bf16 v[98:101], v[192:195], v[216:219], v[98:101]
	v_mfma_f32_16x16x32_bf16 v[82:85], v[184:187], v[238:241], v[82:85]
	v_mfma_f32_16x16x32_bf16 v[66:69], v[192:195], v[238:241], v[66:69]
	s_barrier
	s_add_i32 s0, s0, s37
	v_lshl_add_u64 v[168:169], v[168:169], 0, s[76:77]
	s_mov_b32 m0, s0
	ds_read_b128 v[196:199], v177 offset:49152
	ds_read_b128 v[200:203], v177 offset:50176
	ds_read_b128 v[204:207], v177 offset:51200
	ds_read_b128 v[208:211], v177 offset:52224
	ds_read_b128 v[212:215], v177 offset:53248
	ds_read_b128 v[216:219], v177 offset:54272
	ds_read_b128 v[230:233], v177 offset:55296
	ds_read_b128 v[238:241], v177 offset:56320
	global_load_lds_dwordx4 v[168:169], off
	s_add_i32 m0, s0, 0x2000
	s_add_u32 s56, s56, 0x40080
	v_lshl_add_u64 v[168:169], v[242:243], 0, s[76:77]
	s_addc_u32 s57, s57, 0
	s_add_i32 s0, s83, s37
	global_load_lds_dwordx4 v[168:169], off
	v_lshl_add_u64 v[168:169], s[56:57], 0, v[150:151]
	s_mov_b32 m0, s0
	s_nop 0
	global_load_lds_dwordx4 v[168:169], off
	v_lshl_add_u64 v[168:169], s[56:57], 0, v[146:147]
	s_add_i32 m0, s0, 0x2000
	s_nop 0
	global_load_lds_dwordx4 v[168:169], off
	v_lshl_add_u64 v[168:169], v[244:245], 0, s[76:77]
	s_mov_b32 m0, s67
	s_nop 0
	global_load_lds_dwordx4 v[168:169], off
	v_lshl_add_u64 v[168:169], v[246:247], 0, s[76:77]
	s_mov_b32 m0, s68
	s_nop 0
	global_load_lds_dwordx4 v[168:169], off
	s_waitcnt vmcnt(8)
	s_waitcnt lgkmcnt(0)
	s_barrier
	s_waitcnt lgkmcnt(0)
	v_mfma_f32_16x16x32_bf16 v[62:65], v[74:77], v[196:199], v[62:65]
	v_mfma_f32_16x16x32_bf16 v[54:57], v[90:93], v[196:199], v[54:57]
	v_mfma_f32_16x16x32_bf16 v[46:49], v[74:77], v[204:207], v[46:49]
	v_mfma_f32_16x16x32_bf16 v[38:41], v[90:93], v[204:207], v[38:41]
	v_mfma_f32_16x16x32_bf16 v[30:33], v[74:77], v[212:215], v[30:33]
	v_mfma_f32_16x16x32_bf16 v[22:25], v[90:93], v[212:215], v[22:25]
	v_mfma_f32_16x16x32_bf16 v[14:17], v[74:77], v[230:233], v[14:17]
	v_mfma_f32_16x16x32_bf16 v[6:9], v[90:93], v[230:233], v[6:9]
	v_mfma_f32_16x16x32_bf16 v[62:65], v[78:81], v[200:203], v[62:65]
	v_mfma_f32_16x16x32_bf16 v[54:57], v[94:97], v[200:203], v[54:57]
	v_mfma_f32_16x16x32_bf16 v[46:49], v[78:81], v[208:211], v[46:49]
	v_mfma_f32_16x16x32_bf16 v[38:41], v[94:97], v[208:211], v[38:41]
	v_mfma_f32_16x16x32_bf16 v[30:33], v[78:81], v[216:219], v[30:33]
	v_mfma_f32_16x16x32_bf16 v[22:25], v[94:97], v[216:219], v[22:25]
	v_mfma_f32_16x16x32_bf16 v[14:17], v[78:81], v[238:241], v[14:17]
	v_mfma_f32_16x16x32_bf16 v[6:9], v[94:97], v[238:241], v[6:9]
	v_mfma_f32_16x16x32_bf16 v[58:61], v[180:183], v[196:199], v[58:61]
	v_mfma_f32_16x16x32_bf16 v[50:53], v[188:191], v[196:199], v[50:53]
	v_mfma_f32_16x16x32_bf16 v[42:45], v[180:183], v[204:207], v[42:45]
	v_mfma_f32_16x16x32_bf16 v[34:37], v[188:191], v[204:207], v[34:37]
	v_mfma_f32_16x16x32_bf16 v[26:29], v[180:183], v[212:215], v[26:29]
	v_mfma_f32_16x16x32_bf16 v[18:21], v[188:191], v[212:215], v[18:21]
	v_mfma_f32_16x16x32_bf16 v[10:13], v[180:183], v[230:233], v[10:13]
	v_mfma_f32_16x16x32_bf16 v[2:5], v[188:191], v[230:233], v[2:5]
	v_mfma_f32_16x16x32_bf16 v[58:61], v[184:187], v[200:203], v[58:61]
	v_mfma_f32_16x16x32_bf16 v[50:53], v[192:195], v[200:203], v[50:53]
	v_mfma_f32_16x16x32_bf16 v[42:45], v[184:187], v[208:211], v[42:45]
	v_mfma_f32_16x16x32_bf16 v[34:37], v[192:195], v[208:211], v[34:37]
	v_mfma_f32_16x16x32_bf16 v[26:29], v[184:187], v[216:219], v[26:29]
	v_mfma_f32_16x16x32_bf16 v[18:21], v[192:195], v[216:219], v[18:21]
	v_mfma_f32_16x16x32_bf16 v[10:13], v[184:187], v[238:241], v[10:13]
	v_mfma_f32_16x16x32_bf16 v[2:5], v[192:195], v[238:241], v[2:5]
	s_barrier
	s_add_i32 s82, s82, 2
	s_add_u32 s52, s52, 0x100
	s_addc_u32 s53, s53, 0
	s_add_u32 s73, s73, 0x100
	s_addc_u32 s75, s75, 0
.LBB0_256:
	s_add_u32 s0, s52, 0xfffc0080
	s_addc_u32 s56, s53, -1
	s_add_i32 s83, 0, 0x10000
	s_cmp_eq_u32 s82, 12
	s_cselect_b32 s59, s15, s56
	s_cselect_b32 s58, s20, s0
	s_cselect_b32 s57, s13, s75
	s_cselect_b32 s56, s21, s73
	s_add_i32 s0, 0, 0x14000
	v_add_u32_e32 v94, s83, v171
	v_add_u32_e32 v155, s0, v171
	ds_read_b128 v[74:77], v94
	ds_read_b128 v[78:81], v94 offset:1024
	ds_read_b128 v[90:93], v94 offset:2048
	ds_read_b128 v[94:97], v94 offset:3072
	ds_read_b128 v[180:183], v155
	ds_read_b128 v[184:187], v155 offset:1024
	ds_read_b128 v[188:191], v155 offset:2048
	ds_read_b128 v[192:195], v155 offset:3072
	v_lshl_add_u64 v[168:169], s[52:53], 0, v[164:165]
	s_add_i32 m0, s61, 0xc000
	ds_read_b128 v[196:199], v177
	ds_read_b128 v[200:203], v177 offset:1024
	ds_read_b128 v[204:207], v177 offset:2048
	ds_read_b128 v[208:211], v177 offset:3072
	ds_read_b128 v[212:215], v177 offset:4096
	ds_read_b128 v[216:219], v177 offset:5120
	ds_read_b128 v[230:233], v177 offset:6144
	ds_read_b128 v[238:241], v177 offset:7168
	global_load_lds_dwordx4 v[168:169], off
	v_lshl_add_u64 v[168:169], s[52:53], 0, v[166:167]
	s_add_i32 m0, s61, 0xe000
	s_nop 0
	global_load_lds_dwordx4 v[168:169], off
	s_waitcnt vmcnt(8)
	s_waitcnt lgkmcnt(0)
	s_barrier
	s_waitcnt lgkmcnt(0)
	v_mfma_f32_16x16x32_bf16 v[142:145], v[74:77], v[196:199], v[142:145]
	v_mfma_f32_16x16x32_bf16 v[134:137], v[90:93], v[196:199], v[134:137]
	v_mfma_f32_16x16x32_bf16 v[126:129], v[74:77], v[204:207], v[126:129]
	v_mfma_f32_16x16x32_bf16 v[118:121], v[90:93], v[204:207], v[118:121]
	v_mfma_f32_16x16x32_bf16 v[110:113], v[74:77], v[212:215], v[110:113]
	v_mfma_f32_16x16x32_bf16 v[102:105], v[90:93], v[212:215], v[102:105]
	v_mfma_f32_16x16x32_bf16 v[86:89], v[74:77], v[230:233], v[86:89]
	v_mfma_f32_16x16x32_bf16 v[70:73], v[90:93], v[230:233], v[70:73]
	v_mfma_f32_16x16x32_bf16 v[142:145], v[78:81], v[200:203], v[142:145]
	v_mfma_f32_16x16x32_bf16 v[134:137], v[94:97], v[200:203], v[134:137]
	v_mfma_f32_16x16x32_bf16 v[126:129], v[78:81], v[208:211], v[126:129]
	v_mfma_f32_16x16x32_bf16 v[118:121], v[94:97], v[208:211], v[118:121]
	v_mfma_f32_16x16x32_bf16 v[110:113], v[78:81], v[216:219], v[110:113]
	v_mfma_f32_16x16x32_bf16 v[102:105], v[94:97], v[216:219], v[102:105]
	v_mfma_f32_16x16x32_bf16 v[86:89], v[78:81], v[238:241], v[86:89]
	v_mfma_f32_16x16x32_bf16 v[70:73], v[94:97], v[238:241], v[70:73]
	v_mfma_f32_16x16x32_bf16 v[138:141], v[180:183], v[196:199], v[138:141]
	v_mfma_f32_16x16x32_bf16 v[130:133], v[188:191], v[196:199], v[130:133]
	v_mfma_f32_16x16x32_bf16 v[122:125], v[180:183], v[204:207], v[122:125]
	v_mfma_f32_16x16x32_bf16 v[114:117], v[188:191], v[204:207], v[114:117]
	v_mfma_f32_16x16x32_bf16 v[106:109], v[180:183], v[212:215], v[106:109]
	v_mfma_f32_16x16x32_bf16 v[98:101], v[188:191], v[212:215], v[98:101]
	v_mfma_f32_16x16x32_bf16 v[82:85], v[180:183], v[230:233], v[82:85]
	v_mfma_f32_16x16x32_bf16 v[66:69], v[188:191], v[230:233], v[66:69]
	v_mfma_f32_16x16x32_bf16 v[138:141], v[184:187], v[200:203], v[138:141]
	v_mfma_f32_16x16x32_bf16 v[130:133], v[192:195], v[200:203], v[130:133]
	v_mfma_f32_16x16x32_bf16 v[122:125], v[184:187], v[208:211], v[122:125]
	v_mfma_f32_16x16x32_bf16 v[114:117], v[192:195], v[208:211], v[114:117]
	v_mfma_f32_16x16x32_bf16 v[106:109], v[184:187], v[216:219], v[106:109]
	v_mfma_f32_16x16x32_bf16 v[98:101], v[192:195], v[216:219], v[98:101]
	v_mfma_f32_16x16x32_bf16 v[82:85], v[184:187], v[238:241], v[82:85]
	v_mfma_f32_16x16x32_bf16 v[66:69], v[192:195], v[238:241], v[66:69]
	s_barrier
	s_add_i32 s83, s83, s37
	v_lshl_add_u64 v[168:169], s[56:57], 0, v[150:151]
	s_mov_b32 m0, s83
	ds_read_b128 v[196:199], v177 offset:16384
	ds_read_b128 v[200:203], v177 offset:17408
	ds_read_b128 v[204:207], v177 offset:18432
	ds_read_b128 v[208:211], v177 offset:19456
	ds_read_b128 v[212:215], v177 offset:20480
	ds_read_b128 v[216:219], v177 offset:21504
	ds_read_b128 v[230:233], v177 offset:22528
	ds_read_b128 v[238:241], v177 offset:23552
	global_load_lds_dwordx4 v[168:169], off
	s_add_i32 m0, s83, 0x2000
	s_add_u32 s84, s56, 0x40000
	v_lshl_add_u64 v[242:243], s[56:57], 0, v[146:147]
	s_addc_u32 s85, s57, 0
	s_add_i32 s0, s0, s37
	global_load_lds_dwordx4 v[242:243], off
	v_lshl_add_u64 v[244:245], s[84:85], 0, v[150:151]
	s_mov_b32 m0, s0
	v_lshl_add_u64 v[246:247], s[58:59], 0, v[148:149]
	global_load_lds_dwordx4 v[244:245], off
	v_lshl_add_u64 v[244:245], s[84:85], 0, v[146:147]
	s_add_i32 m0, s0, 0x2000
	s_nop 0
	global_load_lds_dwordx4 v[244:245], off
	v_lshl_add_u64 v[244:245], s[58:59], 0, v[152:153]
	s_mov_b32 m0, s61
	s_nop 0
	global_load_lds_dwordx4 v[244:245], off
	s_mov_b32 m0, s64
	s_nop 0
	global_load_lds_dwordx4 v[246:247], off
	s_waitcnt vmcnt(8)
	s_waitcnt lgkmcnt(0)
	s_barrier
	s_waitcnt lgkmcnt(0)
	v_mfma_f32_16x16x32_bf16 v[62:65], v[74:77], v[196:199], v[62:65]
	v_mfma_f32_16x16x32_bf16 v[54:57], v[90:93], v[196:199], v[54:57]
	v_mfma_f32_16x16x32_bf16 v[46:49], v[74:77], v[204:207], v[46:49]
	v_mfma_f32_16x16x32_bf16 v[38:41], v[90:93], v[204:207], v[38:41]
	v_mfma_f32_16x16x32_bf16 v[30:33], v[74:77], v[212:215], v[30:33]
	v_mfma_f32_16x16x32_bf16 v[22:25], v[90:93], v[212:215], v[22:25]
	v_mfma_f32_16x16x32_bf16 v[14:17], v[74:77], v[230:233], v[14:17]
	v_mfma_f32_16x16x32_bf16 v[6:9], v[90:93], v[230:233], v[6:9]
	v_mfma_f32_16x16x32_bf16 v[62:65], v[78:81], v[200:203], v[62:65]
	v_mfma_f32_16x16x32_bf16 v[54:57], v[94:97], v[200:203], v[54:57]
	v_mfma_f32_16x16x32_bf16 v[46:49], v[78:81], v[208:211], v[46:49]
	v_mfma_f32_16x16x32_bf16 v[38:41], v[94:97], v[208:211], v[38:41]
	v_mfma_f32_16x16x32_bf16 v[30:33], v[78:81], v[216:219], v[30:33]
	v_mfma_f32_16x16x32_bf16 v[22:25], v[94:97], v[216:219], v[22:25]
	v_mfma_f32_16x16x32_bf16 v[14:17], v[78:81], v[238:241], v[14:17]
	v_mfma_f32_16x16x32_bf16 v[6:9], v[94:97], v[238:241], v[6:9]
	v_mfma_f32_16x16x32_bf16 v[58:61], v[180:183], v[196:199], v[58:61]
	v_mfma_f32_16x16x32_bf16 v[50:53], v[188:191], v[196:199], v[50:53]
	v_mfma_f32_16x16x32_bf16 v[42:45], v[180:183], v[204:207], v[42:45]
	v_mfma_f32_16x16x32_bf16 v[34:37], v[188:191], v[204:207], v[34:37]
	v_mfma_f32_16x16x32_bf16 v[26:29], v[180:183], v[212:215], v[26:29]
	v_mfma_f32_16x16x32_bf16 v[18:21], v[188:191], v[212:215], v[18:21]
	v_mfma_f32_16x16x32_bf16 v[10:13], v[180:183], v[230:233], v[10:13]
	v_mfma_f32_16x16x32_bf16 v[2:5], v[188:191], v[230:233], v[2:5]
	v_mfma_f32_16x16x32_bf16 v[58:61], v[184:187], v[200:203], v[58:61]
	v_mfma_f32_16x16x32_bf16 v[50:53], v[192:195], v[200:203], v[50:53]
	v_mfma_f32_16x16x32_bf16 v[42:45], v[184:187], v[208:211], v[42:45]
	v_mfma_f32_16x16x32_bf16 v[34:37], v[192:195], v[208:211], v[34:37]
	v_mfma_f32_16x16x32_bf16 v[26:29], v[184:187], v[216:219], v[26:29]
	v_mfma_f32_16x16x32_bf16 v[18:21], v[192:195], v[216:219], v[18:21]
	v_mfma_f32_16x16x32_bf16 v[10:13], v[184:187], v[238:241], v[10:13]
	v_mfma_f32_16x16x32_bf16 v[2:5], v[192:195], v[238:241], v[2:5]
	s_barrier
	s_add_i32 s0, 0, 0x18000
	s_add_i32 s83, 0, 0x1c000
	v_add_u32_e32 v94, s0, v171
	v_add_u32_e32 v155, s83, v171
	ds_read_b128 v[74:77], v94
	ds_read_b128 v[78:81], v94 offset:1024
	ds_read_b128 v[90:93], v94 offset:2048
	ds_read_b128 v[94:97], v94 offset:3072
	ds_read_b128 v[180:183], v155
	ds_read_b128 v[184:187], v155 offset:1024
	ds_read_b128 v[188:191], v155 offset:2048
	ds_read_b128 v[192:195], v155 offset:3072
	s_add_u32 s58, s58, 0x40000
	s_addc_u32 s59, s59, 0
	s_mov_b32 m0, s65
	v_lshl_add_u64 v[248:249], s[58:59], 0, v[152:153]
	ds_read_b128 v[196:199], v177 offset:32768
	ds_read_b128 v[200:203], v177 offset:33792
	ds_read_b128 v[204:207], v177 offset:34816
	ds_read_b128 v[208:211], v177 offset:35840
	ds_read_b128 v[212:215], v177 offset:36864
	ds_read_b128 v[216:219], v177 offset:37888
	ds_read_b128 v[230:233], v177 offset:38912
	ds_read_b128 v[238:241], v177 offset:39936
	global_load_lds_dwordx4 v[248:249], off
	v_lshl_add_u64 v[248:249], s[58:59], 0, v[148:149]
	s_mov_b32 m0, s66
	s_nop 0
	global_load_lds_dwordx4 v[248:249], off
	s_waitcnt vmcnt(8)
	s_waitcnt lgkmcnt(0)
	s_barrier
	s_waitcnt lgkmcnt(0)
	v_mfma_f32_16x16x32_bf16 v[142:145], v[74:77], v[196:199], v[142:145]
	v_mfma_f32_16x16x32_bf16 v[134:137], v[90:93], v[196:199], v[134:137]
	v_mfma_f32_16x16x32_bf16 v[126:129], v[74:77], v[204:207], v[126:129]
	v_mfma_f32_16x16x32_bf16 v[118:121], v[90:93], v[204:207], v[118:121]
	v_mfma_f32_16x16x32_bf16 v[110:113], v[74:77], v[212:215], v[110:113]
	v_mfma_f32_16x16x32_bf16 v[102:105], v[90:93], v[212:215], v[102:105]
	v_mfma_f32_16x16x32_bf16 v[86:89], v[74:77], v[230:233], v[86:89]
	v_mfma_f32_16x16x32_bf16 v[70:73], v[90:93], v[230:233], v[70:73]
	v_mfma_f32_16x16x32_bf16 v[142:145], v[78:81], v[200:203], v[142:145]
	v_mfma_f32_16x16x32_bf16 v[134:137], v[94:97], v[200:203], v[134:137]
	v_mfma_f32_16x16x32_bf16 v[126:129], v[78:81], v[208:211], v[126:129]
	v_mfma_f32_16x16x32_bf16 v[118:121], v[94:97], v[208:211], v[118:121]
	v_mfma_f32_16x16x32_bf16 v[110:113], v[78:81], v[216:219], v[110:113]
	v_mfma_f32_16x16x32_bf16 v[102:105], v[94:97], v[216:219], v[102:105]
	v_mfma_f32_16x16x32_bf16 v[86:89], v[78:81], v[238:241], v[86:89]
	v_mfma_f32_16x16x32_bf16 v[70:73], v[94:97], v[238:241], v[70:73]
	v_mfma_f32_16x16x32_bf16 v[138:141], v[180:183], v[196:199], v[138:141]
	v_mfma_f32_16x16x32_bf16 v[130:133], v[188:191], v[196:199], v[130:133]
	v_mfma_f32_16x16x32_bf16 v[122:125], v[180:183], v[204:207], v[122:125]
	v_mfma_f32_16x16x32_bf16 v[114:117], v[188:191], v[204:207], v[114:117]
	v_mfma_f32_16x16x32_bf16 v[106:109], v[180:183], v[212:215], v[106:109]
	v_mfma_f32_16x16x32_bf16 v[98:101], v[188:191], v[212:215], v[98:101]
	v_mfma_f32_16x16x32_bf16 v[82:85], v[180:183], v[230:233], v[82:85]
	v_mfma_f32_16x16x32_bf16 v[66:69], v[188:191], v[230:233], v[66:69]
	v_mfma_f32_16x16x32_bf16 v[138:141], v[184:187], v[200:203], v[138:141]
	v_mfma_f32_16x16x32_bf16 v[130:133], v[192:195], v[200:203], v[130:133]
	v_mfma_f32_16x16x32_bf16 v[122:125], v[184:187], v[208:211], v[122:125]
	v_mfma_f32_16x16x32_bf16 v[114:117], v[192:195], v[208:211], v[114:117]
	v_mfma_f32_16x16x32_bf16 v[106:109], v[184:187], v[216:219], v[106:109]
	v_mfma_f32_16x16x32_bf16 v[98:101], v[192:195], v[216:219], v[98:101]
	v_mfma_f32_16x16x32_bf16 v[82:85], v[184:187], v[238:241], v[82:85]
	v_mfma_f32_16x16x32_bf16 v[66:69], v[192:195], v[238:241], v[66:69]
	s_barrier
	s_add_i32 s0, s0, s37
	v_lshl_add_u64 v[168:169], v[168:169], 0, s[76:77]
	s_mov_b32 m0, s0
	ds_read_b128 v[196:199], v177 offset:49152
	ds_read_b128 v[200:203], v177 offset:50176
	ds_read_b128 v[204:207], v177 offset:51200
	ds_read_b128 v[208:211], v177 offset:52224
	ds_read_b128 v[212:215], v177 offset:53248
	ds_read_b128 v[216:219], v177 offset:54272
	ds_read_b128 v[230:233], v177 offset:55296
	ds_read_b128 v[238:241], v177 offset:56320
	global_load_lds_dwordx4 v[168:169], off
	s_add_i32 m0, s0, 0x2000
	s_add_u32 s56, s56, 0x40080
	v_lshl_add_u64 v[168:169], v[242:243], 0, s[76:77]
	s_addc_u32 s57, s57, 0
	s_add_i32 s0, s83, s37
	global_load_lds_dwordx4 v[168:169], off
	v_lshl_add_u64 v[168:169], s[56:57], 0, v[150:151]
	s_mov_b32 m0, s0
	s_nop 0
	global_load_lds_dwordx4 v[168:169], off
	v_lshl_add_u64 v[168:169], s[56:57], 0, v[146:147]
	s_add_i32 m0, s0, 0x2000
	s_nop 0
	global_load_lds_dwordx4 v[168:169], off
	v_lshl_add_u64 v[168:169], v[244:245], 0, s[76:77]
	s_mov_b32 m0, s67
	s_nop 0
	global_load_lds_dwordx4 v[168:169], off
	v_lshl_add_u64 v[168:169], v[246:247], 0, s[76:77]
	s_mov_b32 m0, s68
	s_nop 0
	global_load_lds_dwordx4 v[168:169], off
	s_waitcnt vmcnt(8)
	s_waitcnt lgkmcnt(0)
	s_barrier
	s_waitcnt lgkmcnt(0)
	v_mfma_f32_16x16x32_bf16 v[62:65], v[74:77], v[196:199], v[62:65]
	v_mfma_f32_16x16x32_bf16 v[54:57], v[90:93], v[196:199], v[54:57]
	v_mfma_f32_16x16x32_bf16 v[46:49], v[74:77], v[204:207], v[46:49]
	v_mfma_f32_16x16x32_bf16 v[38:41], v[90:93], v[204:207], v[38:41]
	v_mfma_f32_16x16x32_bf16 v[30:33], v[74:77], v[212:215], v[30:33]
	v_mfma_f32_16x16x32_bf16 v[22:25], v[90:93], v[212:215], v[22:25]
	v_mfma_f32_16x16x32_bf16 v[14:17], v[74:77], v[230:233], v[14:17]
	v_mfma_f32_16x16x32_bf16 v[6:9], v[90:93], v[230:233], v[6:9]
	v_mfma_f32_16x16x32_bf16 v[62:65], v[78:81], v[200:203], v[62:65]
	v_mfma_f32_16x16x32_bf16 v[54:57], v[94:97], v[200:203], v[54:57]
	v_mfma_f32_16x16x32_bf16 v[46:49], v[78:81], v[208:211], v[46:49]
	v_mfma_f32_16x16x32_bf16 v[38:41], v[94:97], v[208:211], v[38:41]
	v_mfma_f32_16x16x32_bf16 v[30:33], v[78:81], v[216:219], v[30:33]
	v_mfma_f32_16x16x32_bf16 v[22:25], v[94:97], v[216:219], v[22:25]
	v_mfma_f32_16x16x32_bf16 v[14:17], v[78:81], v[238:241], v[14:17]
	v_mfma_f32_16x16x32_bf16 v[6:9], v[94:97], v[238:241], v[6:9]
	v_mfma_f32_16x16x32_bf16 v[58:61], v[180:183], v[196:199], v[58:61]
	v_mfma_f32_16x16x32_bf16 v[50:53], v[188:191], v[196:199], v[50:53]
	v_mfma_f32_16x16x32_bf16 v[42:45], v[180:183], v[204:207], v[42:45]
	v_mfma_f32_16x16x32_bf16 v[34:37], v[188:191], v[204:207], v[34:37]
	v_mfma_f32_16x16x32_bf16 v[26:29], v[180:183], v[212:215], v[26:29]
	v_mfma_f32_16x16x32_bf16 v[18:21], v[188:191], v[212:215], v[18:21]
	v_mfma_f32_16x16x32_bf16 v[10:13], v[180:183], v[230:233], v[10:13]
	v_mfma_f32_16x16x32_bf16 v[2:5], v[188:191], v[230:233], v[2:5]
	v_mfma_f32_16x16x32_bf16 v[58:61], v[184:187], v[200:203], v[58:61]
	v_mfma_f32_16x16x32_bf16 v[50:53], v[192:195], v[200:203], v[50:53]
	v_mfma_f32_16x16x32_bf16 v[42:45], v[184:187], v[208:211], v[42:45]
	v_mfma_f32_16x16x32_bf16 v[34:37], v[192:195], v[208:211], v[34:37]
	v_mfma_f32_16x16x32_bf16 v[26:29], v[184:187], v[216:219], v[26:29]
	v_mfma_f32_16x16x32_bf16 v[18:21], v[192:195], v[216:219], v[18:21]
	v_mfma_f32_16x16x32_bf16 v[10:13], v[184:187], v[238:241], v[10:13]
	v_mfma_f32_16x16x32_bf16 v[2:5], v[192:195], v[238:241], v[2:5]
	s_barrier
	s_add_i32 s82, s82, 2
	s_add_u32 s52, s52, 0x100
	s_addc_u32 s53, s53, 0
	s_add_u32 s73, s73, 0x100
	s_addc_u32 s75, s75, 0
	s_cmp_gt_u32 s82, 13
	s_cbranch_scc0 .LBB0_256
	s_and_b64 vcc, exec, s[10:11]
	s_cbranch_vccz .LBB0_259
	s_barrier

.LBB0_267:
	v_or_b32_e32 v82, s8, v1
	v_and_b32_e32 v66, 63, v16
	v_lshlrev_b32_e32 v3, 6, v82
	s_movk_i32 s0, 0x3c0
	v_lshlrev_b32_e32 v16, 2, v82
	v_and_or_b32 v3, v3, s0, v18
	s_lshl_b32 s0, s3, 13
	v_and_b32_e32 v16, 32, v16
	v_bitop3_b32 v16, v3, s0, v16 bitop3:0xde
	v_lshl_or_b32 v3, v1, 6, v18
	s_lshl_b32 s0, s14, 12
	v_and_b32_e32 v2, 32, v2
	v_bitop3_b32 v67, v3, s0, v2 bitop3:0xde
	s_add_i32 m0, s35, 0x18000
	v_lshl_add_u64 v[2:3], v[10:11], 0, s[76:77]
	s_lshl_b32 s21, s14, 5
	s_waitcnt vmcnt(2)
	s_barrier
	global_load_lds_dwordx4 v[2:3], off
	v_lshl_add_u64 v[2:3], v[8:9], 0, s[76:77]
	s_add_i32 m0, s35, 0x1a000
	s_add_i32 s37, s35, 0x8000
	s_add_i32 s38, s35, 0xa000
	global_load_lds_dwordx4 v[2:3], off
	v_lshl_add_u64 v[2:3], v[6:7], 0, s[76:77]
	s_mov_b32 m0, s37
	s_add_u32 s8, s4, 0x40080
	global_load_lds_dwordx4 v[2:3], off
	v_lshl_add_u64 v[2:3], v[4:5], 0, s[76:77]
	s_mov_b32 m0, s38
	s_addc_u32 s9, s5, 0
	global_load_lds_dwordx4 v[2:3], off
	s_add_i32 m0, s35, 0x1c000
	v_lshl_add_u64 v[2:3], s[8:9], 0, v[50:51]
	global_load_lds_dwordx4 v[2:3], off
	v_lshl_add_u64 v[2:3], s[8:9], 0, v[46:47]
	s_add_i32 m0, s35, 0x1e000
	v_readlane_b32 s0, v254, 53
	global_load_lds_dwordx4 v[2:3], off
	v_lshlrev_b32_e32 v2, 14, v12
	v_and_b32_e32 v2, 0xffff8000, v2
	v_lshl_add_u32 v2, v13, 11, v2
	v_and_b32_e32 v3, 1, v12
	s_add_u32 s8, s26, s0
	v_lshl_or_b32 v2, v3, 6, v2
	s_addc_u32 s9, s1, 0
	v_lshl_add_u32 v2, v14, 1, v2
	v_mov_b32_e32 v3, v0
	v_lshl_add_u64 v[62:63], s[8:9], 0, v[2:3]
	v_lshlrev_b32_e32 v2, 14, v17
	v_and_b32_e32 v2, 0xffff8000, v2
	v_lshl_add_u32 v2, v15, 11, v2
	v_and_b32_e32 v3, 1, v17
	v_readlane_b32 s0, v254, 52
	v_lshl_or_b32 v2, v3, 6, v2
	s_add_u32 s40, s26, s0
	v_lshl_add_u32 v2, v19, 1, v2
	v_mov_b32_e32 v3, v0
	s_addc_u32 s41, s1, 0
	v_readlane_b32 s0, v254, 54
	v_lshl_add_u64 v[64:65], s[8:9], 0, v[2:3]
	s_add_u32 s0, s26, s0
	v_readlane_b32 s8, v254, 55
	s_addc_u32 s8, s1, s8
	s_add_u32 s1, s27, s30
	s_waitcnt vmcnt(6)
	s_addc_u32 s9, 0, 0
	s_add_u32 s1, s0, s1
	s_addc_u32 s26, s8, s9
	s_mov_b32 s27, -2
	s_mov_b64 s[8:9], 0
	v_add_u32_e32 v68, 0, v16
	s_barrier
	s_add_u32 s0, s40, s8
	s_addc_u32 s10, s41, s9
	s_add_u32 s0, s0, 0x7c00100
	s_addc_u32 s10, s10, 0
	s_add_u32 s30, s1, s8
	s_addc_u32 s11, s26, s9
	s_add_i32 s42, 0, 0x10000
	s_cmpk_eq_i32 s8, 0x700
	s_cselect_b32 s13, s7, s10
	s_cselect_b32 s12, s6, s0
	v_add_u32_e32 v69, s42, v67
	s_cselect_b32 s11, s5, s11
	s_cselect_b32 s10, s4, s30
	s_add_i32 s0, 0, 0x14000
	ds_read_b128 v[84:87], v69
	ds_read_b128 v[88:91], v69 offset:1024
	ds_read_b128 v[92:95], v69 offset:2048
	ds_read_b128 v[96:99], v69 offset:3072
	v_add_u32_e32 v69, s0, v67
	ds_read_b128 v[100:103], v69
	ds_read_b128 v[104:107], v69 offset:1024
	ds_read_b128 v[108:111], v69 offset:2048
	ds_read_b128 v[112:115], v69 offset:3072
	v_lshl_add_u64 v[148:149], v[64:65], 0, s[8:9]
	s_add_i32 m0, s35, 0xc000
	ds_read_b128 v[116:119], v68
	ds_read_b128 v[120:123], v68 offset:1024
	ds_read_b128 v[124:127], v68 offset:2048
	ds_read_b128 v[128:131], v68 offset:3072
	ds_read_b128 v[132:135], v68 offset:4096
	ds_read_b128 v[136:139], v68 offset:5120
	ds_read_b128 v[140:143], v68 offset:6144
	ds_read_b128 v[144:147], v68 offset:7168
	global_load_lds_dwordx4 v[148:149], off
	v_lshl_add_u64 v[148:149], v[62:63], 0, s[8:9]
	s_add_i32 m0, s35, 0xe000
	s_nop 0
	global_load_lds_dwordx4 v[148:149], off
	s_waitcnt vmcnt(8)
	s_waitcnt lgkmcnt(0)
	s_barrier
	s_waitcnt lgkmcnt(0)
	v_mfma_f32_16x16x32_bf16 v[78:81], v[84:87], v[116:119], 0
	v_mfma_f32_16x16x32_bf16 v[70:73], v[92:95], v[116:119], 0
	v_mfma_f32_16x16x32_bf16 v[54:57], v[84:87], v[124:127], 0
	v_mfma_f32_16x16x32_bf16 v[38:41], v[92:95], v[124:127], 0
	v_mfma_f32_16x16x32_bf16 v[30:33], v[84:87], v[132:135], 0
	v_mfma_f32_16x16x32_bf16 v[22:25], v[92:95], v[132:135], 0
	v_mfma_f32_16x16x32_bf16 v[14:17], v[84:87], v[140:143], 0
	v_mfma_f32_16x16x32_bf16 v[6:9], v[92:95], v[140:143], 0
	v_mfma_f32_16x16x32_bf16 v[78:81], v[88:91], v[120:123], v[78:81]
	v_mfma_f32_16x16x32_bf16 v[70:73], v[96:99], v[120:123], v[70:73]
	v_mfma_f32_16x16x32_bf16 v[54:57], v[88:91], v[128:131], v[54:57]
	v_mfma_f32_16x16x32_bf16 v[38:41], v[96:99], v[128:131], v[38:41]
	v_mfma_f32_16x16x32_bf16 v[30:33], v[88:91], v[136:139], v[30:33]
	v_mfma_f32_16x16x32_bf16 v[22:25], v[96:99], v[136:139], v[22:25]
	v_mfma_f32_16x16x32_bf16 v[14:17], v[88:91], v[144:147], v[14:17]
	v_mfma_f32_16x16x32_bf16 v[6:9], v[96:99], v[144:147], v[6:9]
	v_mfma_f32_16x16x32_bf16 v[74:77], v[100:103], v[116:119], 0
	v_mfma_f32_16x16x32_bf16 v[58:61], v[108:111], v[116:119], 0
	v_mfma_f32_16x16x32_bf16 v[42:45], v[100:103], v[124:127], 0
	v_mfma_f32_16x16x32_bf16 v[34:37], v[108:111], v[124:127], 0
	v_mfma_f32_16x16x32_bf16 v[26:29], v[100:103], v[132:135], 0
	v_mfma_f32_16x16x32_bf16 v[18:21], v[108:111], v[132:135], 0
	v_mfma_f32_16x16x32_bf16 v[10:13], v[100:103], v[140:143], 0
	v_mfma_f32_16x16x32_bf16 v[2:5], v[108:111], v[140:143], 0
	v_mfma_f32_16x16x32_bf16 v[74:77], v[104:107], v[120:123], v[74:77]
	v_mfma_f32_16x16x32_bf16 v[58:61], v[112:115], v[120:123], v[58:61]
	v_mfma_f32_16x16x32_bf16 v[42:45], v[104:107], v[128:131], v[42:45]
	v_mfma_f32_16x16x32_bf16 v[34:37], v[112:115], v[128:131], v[34:37]
	v_mfma_f32_16x16x32_bf16 v[26:29], v[104:107], v[136:139], v[26:29]
	v_mfma_f32_16x16x32_bf16 v[18:21], v[112:115], v[136:139], v[18:21]
	v_mfma_f32_16x16x32_bf16 v[10:13], v[104:107], v[144:147], v[10:13]
	v_mfma_f32_16x16x32_bf16 v[2:5], v[112:115], v[144:147], v[2:5]
	s_barrier
	s_add_i32 s30, s42, s20
	v_lshl_add_u64 v[148:149], s[10:11], 0, v[50:51]
	s_mov_b32 m0, s30
	v_lshl_add_u64 v[150:151], s[10:11], 0, v[46:47]
	global_load_lds_dwordx4 v[148:149], off
	s_add_i32 m0, s30, 0x2000
	s_add_u32 s42, s10, 0x40000
	s_addc_u32 s43, s11, 0
	s_add_i32 s0, s0, s20
	global_load_lds_dwordx4 v[150:151], off
	v_lshl_add_u64 v[84:85], s[42:43], 0, v[50:51]
	s_mov_b32 m0, s0
	v_lshl_add_u64 v[152:153], s[12:13], 0, v[52:53]
	global_load_lds_dwordx4 v[84:85], off
	v_lshl_add_u64 v[84:85], s[42:43], 0, v[46:47]
	s_add_i32 m0, s0, 0x2000
	v_lshl_add_u64 v[154:155], s[12:13], 0, v[48:49]
	global_load_lds_dwordx4 v[84:85], off
	s_mov_b32 m0, s35
	s_nop 0
	global_load_lds_dwordx4 v[152:153], off
	s_mov_b32 m0, s31
	s_nop 0
	global_load_lds_dwordx4 v[154:155], off
	s_waitcnt vmcnt(8)
	s_waitcnt lgkmcnt(0)
	s_barrier
	s_barrier
	s_add_i32 s0, 0, 0x18000
	v_add_u32_e32 v69, s0, v67
	s_add_i32 s12, 0, 0x1c000
	ds_read_b128 v[84:87], v69
	ds_read_b128 v[88:91], v69 offset:1024
	ds_read_b128 v[92:95], v69 offset:2048
	ds_read_b128 v[96:99], v69 offset:3072
	v_add_u32_e32 v69, s12, v67
	ds_read_b128 v[100:103], v69
	ds_read_b128 v[104:107], v69 offset:1024
	ds_read_b128 v[108:111], v69 offset:2048
	ds_read_b128 v[112:115], v69 offset:3072
	s_mov_b32 m0, s34
	ds_read_b128 v[116:119], v68 offset:32768
	ds_read_b128 v[120:123], v68 offset:33792
	ds_read_b128 v[124:127], v68 offset:34816
	ds_read_b128 v[128:131], v68 offset:35840
	ds_read_b128 v[132:135], v68 offset:36864
	ds_read_b128 v[136:139], v68 offset:37888
	ds_read_b128 v[140:143], v68 offset:38912
	ds_read_b128 v[144:147], v68 offset:39936
	global_load_lds_dwordx4 v[152:153], off
	s_mov_b32 m0, s36
	s_nop 0
	global_load_lds_dwordx4 v[154:155], off
	s_waitcnt vmcnt(8)
	s_waitcnt lgkmcnt(0)
	s_barrier
	s_waitcnt lgkmcnt(0)
	v_mfma_f32_16x16x32_bf16 v[78:81], v[84:87], v[116:119], v[78:81]
	v_mfma_f32_16x16x32_bf16 v[70:73], v[92:95], v[116:119], v[70:73]
	v_mfma_f32_16x16x32_bf16 v[54:57], v[84:87], v[124:127], v[54:57]
	v_mfma_f32_16x16x32_bf16 v[38:41], v[92:95], v[124:127], v[38:41]
	v_mfma_f32_16x16x32_bf16 v[30:33], v[84:87], v[132:135], v[30:33]
	v_mfma_f32_16x16x32_bf16 v[22:25], v[92:95], v[132:135], v[22:25]
	v_mfma_f32_16x16x32_bf16 v[14:17], v[84:87], v[140:143], v[14:17]
	v_mfma_f32_16x16x32_bf16 v[6:9], v[92:95], v[140:143], v[6:9]
	v_mfma_f32_16x16x32_bf16 v[78:81], v[88:91], v[120:123], v[78:81]
	v_mfma_f32_16x16x32_bf16 v[70:73], v[96:99], v[120:123], v[70:73]
	v_mfma_f32_16x16x32_bf16 v[54:57], v[88:91], v[128:131], v[54:57]
	v_mfma_f32_16x16x32_bf16 v[38:41], v[96:99], v[128:131], v[38:41]
	v_mfma_f32_16x16x32_bf16 v[30:33], v[88:91], v[136:139], v[30:33]
	v_mfma_f32_16x16x32_bf16 v[22:25], v[96:99], v[136:139], v[22:25]
	v_mfma_f32_16x16x32_bf16 v[14:17], v[88:91], v[144:147], v[14:17]
	v_mfma_f32_16x16x32_bf16 v[6:9], v[96:99], v[144:147], v[6:9]
	v_mfma_f32_16x16x32_bf16 v[74:77], v[100:103], v[116:119], v[74:77]
	v_mfma_f32_16x16x32_bf16 v[58:61], v[108:111], v[116:119], v[58:61]
	v_mfma_f32_16x16x32_bf16 v[42:45], v[100:103], v[124:127], v[42:45]
	v_mfma_f32_16x16x32_bf16 v[34:37], v[108:111], v[124:127], v[34:37]
	v_mfma_f32_16x16x32_bf16 v[26:29], v[100:103], v[132:135], v[26:29]
	v_mfma_f32_16x16x32_bf16 v[18:21], v[108:111], v[132:135], v[18:21]
	v_mfma_f32_16x16x32_bf16 v[10:13], v[100:103], v[140:143], v[10:13]
	v_mfma_f32_16x16x32_bf16 v[2:5], v[108:111], v[140:143], v[2:5]
	v_mfma_f32_16x16x32_bf16 v[74:77], v[104:107], v[120:123], v[74:77]
	v_mfma_f32_16x16x32_bf16 v[58:61], v[112:115], v[120:123], v[58:61]
	v_mfma_f32_16x16x32_bf16 v[42:45], v[104:107], v[128:131], v[42:45]
	v_mfma_f32_16x16x32_bf16 v[34:37], v[112:115], v[128:131], v[34:37]
	v_mfma_f32_16x16x32_bf16 v[26:29], v[104:107], v[136:139], v[26:29]
	v_mfma_f32_16x16x32_bf16 v[18:21], v[112:115], v[136:139], v[18:21]
	v_mfma_f32_16x16x32_bf16 v[10:13], v[104:107], v[144:147], v[10:13]
	v_mfma_f32_16x16x32_bf16 v[2:5], v[112:115], v[144:147], v[2:5]
	s_barrier
	s_add_i32 s0, s0, s20
	v_lshl_add_u64 v[84:85], v[148:149], 0, s[76:77]
	s_mov_b32 m0, s0
	s_nop 0
	global_load_lds_dwordx4 v[84:85], off
	s_add_i32 m0, s0, 0x2000
	s_add_u32 s10, s10, 0x40080
	v_lshl_add_u64 v[84:85], v[150:151], 0, s[76:77]
	s_addc_u32 s11, s11, 0
	s_add_i32 s0, s12, s20
	global_load_lds_dwordx4 v[84:85], off
	v_lshl_add_u64 v[84:85], s[10:11], 0, v[50:51]
	s_mov_b32 m0, s0
	s_nop 0
	global_load_lds_dwordx4 v[84:85], off
	v_lshl_add_u64 v[84:85], s[10:11], 0, v[46:47]
	s_add_i32 m0, s0, 0x2000
	s_nop 0
	global_load_lds_dwordx4 v[84:85], off
	v_lshl_add_u64 v[84:85], v[152:153], 0, s[76:77]
	s_mov_b32 m0, s37
	s_nop 0
	global_load_lds_dwordx4 v[84:85], off
	v_lshl_add_u64 v[84:85], v[154:155], 0, s[76:77]
	s_mov_b32 m0, s38
	s_nop 0
	global_load_lds_dwordx4 v[84:85], off
	s_waitcnt vmcnt(8)
	s_waitcnt lgkmcnt(0)
	s_barrier
	s_barrier
	s_add_i32 s27, s27, 2
	s_add_u32 s8, s8, 0x100
	s_addc_u32 s9, s9, 0
.LBB0_268:
	s_add_u32 s0, s40, s8
	s_addc_u32 s10, s41, s9
	s_add_u32 s0, s0, 0x7c00100
	s_addc_u32 s10, s10, 0
	s_add_u32 s30, s1, s8
	s_addc_u32 s11, s26, s9
	s_add_i32 s42, 0, 0x10000
	s_cmpk_eq_i32 s8, 0x700
	s_cselect_b32 s13, s7, s10
	s_cselect_b32 s12, s6, s0
	v_add_u32_e32 v69, s42, v67
	s_cselect_b32 s11, s5, s11
	s_cselect_b32 s10, s4, s30
	s_add_i32 s0, 0, 0x14000
	ds_read_b128 v[84:87], v69
	ds_read_b128 v[88:91], v69 offset:1024
	ds_read_b128 v[92:95], v69 offset:2048
	ds_read_b128 v[96:99], v69 offset:3072
	v_add_u32_e32 v69, s0, v67
	ds_read_b128 v[100:103], v69
	ds_read_b128 v[104:107], v69 offset:1024
	ds_read_b128 v[108:111], v69 offset:2048
	ds_read_b128 v[112:115], v69 offset:3072
	v_lshl_add_u64 v[148:149], v[64:65], 0, s[8:9]
	s_add_i32 m0, s35, 0xc000
	ds_read_b128 v[116:119], v68
	ds_read_b128 v[120:123], v68 offset:1024
	ds_read_b128 v[124:127], v68 offset:2048
	ds_read_b128 v[128:131], v68 offset:3072
	ds_read_b128 v[132:135], v68 offset:4096
	ds_read_b128 v[136:139], v68 offset:5120
	ds_read_b128 v[140:143], v68 offset:6144
	ds_read_b128 v[144:147], v68 offset:7168
	global_load_lds_dwordx4 v[148:149], off
	v_lshl_add_u64 v[148:149], v[62:63], 0, s[8:9]
	s_add_i32 m0, s35, 0xe000
	s_nop 0
	global_load_lds_dwordx4 v[148:149], off
	s_waitcnt vmcnt(8)
	s_waitcnt lgkmcnt(0)
	s_barrier
	s_waitcnt lgkmcnt(0)
	v_mfma_f32_16x16x32_bf16 v[78:81], v[84:87], v[116:119], v[78:81]
	v_mfma_f32_16x16x32_bf16 v[70:73], v[92:95], v[116:119], v[70:73]
	v_mfma_f32_16x16x32_bf16 v[54:57], v[84:87], v[124:127], v[54:57]
	v_mfma_f32_16x16x32_bf16 v[38:41], v[92:95], v[124:127], v[38:41]
	v_mfma_f32_16x16x32_bf16 v[30:33], v[84:87], v[132:135], v[30:33]
	v_mfma_f32_16x16x32_bf16 v[22:25], v[92:95], v[132:135], v[22:25]
	v_mfma_f32_16x16x32_bf16 v[14:17], v[84:87], v[140:143], v[14:17]
	v_mfma_f32_16x16x32_bf16 v[6:9], v[92:95], v[140:143], v[6:9]
	v_mfma_f32_16x16x32_bf16 v[78:81], v[88:91], v[120:123], v[78:81]
	v_mfma_f32_16x16x32_bf16 v[70:73], v[96:99], v[120:123], v[70:73]
	v_mfma_f32_16x16x32_bf16 v[54:57], v[88:91], v[128:131], v[54:57]
	v_mfma_f32_16x16x32_bf16 v[38:41], v[96:99], v[128:131], v[38:41]
	v_mfma_f32_16x16x32_bf16 v[30:33], v[88:91], v[136:139], v[30:33]
	v_mfma_f32_16x16x32_bf16 v[22:25], v[96:99], v[136:139], v[22:25]
	v_mfma_f32_16x16x32_bf16 v[14:17], v[88:91], v[144:147], v[14:17]
	v_mfma_f32_16x16x32_bf16 v[6:9], v[96:99], v[144:147], v[6:9]
	v_mfma_f32_16x16x32_bf16 v[74:77], v[100:103], v[116:119], v[74:77]
	v_mfma_f32_16x16x32_bf16 v[58:61], v[108:111], v[116:119], v[58:61]
	v_mfma_f32_16x16x32_bf16 v[42:45], v[100:103], v[124:127], v[42:45]
	v_mfma_f32_16x16x32_bf16 v[34:37], v[108:111], v[124:127], v[34:37]
	v_mfma_f32_16x16x32_bf16 v[26:29], v[100:103], v[132:135], v[26:29]
	v_mfma_f32_16x16x32_bf16 v[18:21], v[108:111], v[132:135], v[18:21]
	v_mfma_f32_16x16x32_bf16 v[10:13], v[100:103], v[140:143], v[10:13]
	v_mfma_f32_16x16x32_bf16 v[2:5], v[108:111], v[140:143], v[2:5]
	v_mfma_f32_16x16x32_bf16 v[74:77], v[104:107], v[120:123], v[74:77]
	v_mfma_f32_16x16x32_bf16 v[58:61], v[112:115], v[120:123], v[58:61]
	v_mfma_f32_16x16x32_bf16 v[42:45], v[104:107], v[128:131], v[42:45]
	v_mfma_f32_16x16x32_bf16 v[34:37], v[112:115], v[128:131], v[34:37]
	v_mfma_f32_16x16x32_bf16 v[26:29], v[104:107], v[136:139], v[26:29]
	v_mfma_f32_16x16x32_bf16 v[18:21], v[112:115], v[136:139], v[18:21]
	v_mfma_f32_16x16x32_bf16 v[10:13], v[104:107], v[144:147], v[10:13]
	v_mfma_f32_16x16x32_bf16 v[2:5], v[112:115], v[144:147], v[2:5]
	s_barrier
	s_add_i32 s30, s42, s20
	v_lshl_add_u64 v[148:149], s[10:11], 0, v[50:51]
	s_mov_b32 m0, s30
	v_lshl_add_u64 v[150:151], s[10:11], 0, v[46:47]
	global_load_lds_dwordx4 v[148:149], off
	s_add_i32 m0, s30, 0x2000
	s_add_u32 s42, s10, 0x40000
	s_addc_u32 s43, s11, 0
	s_add_i32 s0, s0, s20
	global_load_lds_dwordx4 v[150:151], off
	v_lshl_add_u64 v[84:85], s[42:43], 0, v[50:51]
	s_mov_b32 m0, s0
	v_lshl_add_u64 v[152:153], s[12:13], 0, v[52:53]
	global_load_lds_dwordx4 v[84:85], off
	v_lshl_add_u64 v[84:85], s[42:43], 0, v[46:47]
	s_add_i32 m0, s0, 0x2000
	v_lshl_add_u64 v[154:155], s[12:13], 0, v[48:49]
	global_load_lds_dwordx4 v[84:85], off
	s_mov_b32 m0, s35
	s_nop 0
	global_load_lds_dwordx4 v[152:153], off
	s_mov_b32 m0, s31
	s_nop 0
	global_load_lds_dwordx4 v[154:155], off
	s_waitcnt vmcnt(8)
	s_waitcnt lgkmcnt(0)
	s_barrier
	s_barrier
	s_add_i32 s0, 0, 0x18000
	v_add_u32_e32 v69, s0, v67
	s_add_i32 s12, 0, 0x1c000
	ds_read_b128 v[84:87], v69
	ds_read_b128 v[88:91], v69 offset:1024
	ds_read_b128 v[92:95], v69 offset:2048
	ds_read_b128 v[96:99], v69 offset:3072
	v_add_u32_e32 v69, s12, v67
	ds_read_b128 v[100:103], v69
	ds_read_b128 v[104:107], v69 offset:1024
	ds_read_b128 v[108:111], v69 offset:2048
	ds_read_b128 v[112:115], v69 offset:3072
	s_mov_b32 m0, s34
	ds_read_b128 v[116:119], v68 offset:32768
	ds_read_b128 v[120:123], v68 offset:33792
	ds_read_b128 v[124:127], v68 offset:34816
	ds_read_b128 v[128:131], v68 offset:35840
	ds_read_b128 v[132:135], v68 offset:36864
	ds_read_b128 v[136:139], v68 offset:37888
	ds_read_b128 v[140:143], v68 offset:38912
	ds_read_b128 v[144:147], v68 offset:39936
	global_load_lds_dwordx4 v[152:153], off
	s_mov_b32 m0, s36
	s_nop 0
	global_load_lds_dwordx4 v[154:155], off
	s_waitcnt vmcnt(8)
	s_waitcnt lgkmcnt(0)
	s_barrier
	s_waitcnt lgkmcnt(0)
	v_mfma_f32_16x16x32_bf16 v[78:81], v[84:87], v[116:119], v[78:81]
	v_mfma_f32_16x16x32_bf16 v[70:73], v[92:95], v[116:119], v[70:73]
	v_mfma_f32_16x16x32_bf16 v[54:57], v[84:87], v[124:127], v[54:57]
	v_mfma_f32_16x16x32_bf16 v[38:41], v[92:95], v[124:127], v[38:41]
	v_mfma_f32_16x16x32_bf16 v[30:33], v[84:87], v[132:135], v[30:33]
	v_mfma_f32_16x16x32_bf16 v[22:25], v[92:95], v[132:135], v[22:25]
	v_mfma_f32_16x16x32_bf16 v[14:17], v[84:87], v[140:143], v[14:17]
	v_mfma_f32_16x16x32_bf16 v[6:9], v[92:95], v[140:143], v[6:9]
	v_mfma_f32_16x16x32_bf16 v[78:81], v[88:91], v[120:123], v[78:81]
	v_mfma_f32_16x16x32_bf16 v[70:73], v[96:99], v[120:123], v[70:73]
	v_mfma_f32_16x16x32_bf16 v[54:57], v[88:91], v[128:131], v[54:57]
	v_mfma_f32_16x16x32_bf16 v[38:41], v[96:99], v[128:131], v[38:41]
	v_mfma_f32_16x16x32_bf16 v[30:33], v[88:91], v[136:139], v[30:33]
	v_mfma_f32_16x16x32_bf16 v[22:25], v[96:99], v[136:139], v[22:25]
	v_mfma_f32_16x16x32_bf16 v[14:17], v[88:91], v[144:147], v[14:17]
	v_mfma_f32_16x16x32_bf16 v[6:9], v[96:99], v[144:147], v[6:9]
	v_mfma_f32_16x16x32_bf16 v[74:77], v[100:103], v[116:119], v[74:77]
	v_mfma_f32_16x16x32_bf16 v[58:61], v[108:111], v[116:119], v[58:61]
	v_mfma_f32_16x16x32_bf16 v[42:45], v[100:103], v[124:127], v[42:45]
	v_mfma_f32_16x16x32_bf16 v[34:37], v[108:111], v[124:127], v[34:37]
	v_mfma_f32_16x16x32_bf16 v[26:29], v[100:103], v[132:135], v[26:29]
	v_mfma_f32_16x16x32_bf16 v[18:21], v[108:111], v[132:135], v[18:21]
	v_mfma_f32_16x16x32_bf16 v[10:13], v[100:103], v[140:143], v[10:13]
	v_mfma_f32_16x16x32_bf16 v[2:5], v[108:111], v[140:143], v[2:5]
	v_mfma_f32_16x16x32_bf16 v[74:77], v[104:107], v[120:123], v[74:77]
	v_mfma_f32_16x16x32_bf16 v[58:61], v[112:115], v[120:123], v[58:61]
	v_mfma_f32_16x16x32_bf16 v[42:45], v[104:107], v[128:131], v[42:45]
	v_mfma_f32_16x16x32_bf16 v[34:37], v[112:115], v[128:131], v[34:37]
	v_mfma_f32_16x16x32_bf16 v[26:29], v[104:107], v[136:139], v[26:29]
	v_mfma_f32_16x16x32_bf16 v[18:21], v[112:115], v[136:139], v[18:21]
	v_mfma_f32_16x16x32_bf16 v[10:13], v[104:107], v[144:147], v[10:13]
	v_mfma_f32_16x16x32_bf16 v[2:5], v[112:115], v[144:147], v[2:5]
	s_barrier
	s_add_i32 s0, s0, s20
	v_lshl_add_u64 v[84:85], v[148:149], 0, s[76:77]
	s_mov_b32 m0, s0
	s_nop 0
	global_load_lds_dwordx4 v[84:85], off
	s_add_i32 m0, s0, 0x2000
	s_add_u32 s10, s10, 0x40080
	v_lshl_add_u64 v[84:85], v[150:151], 0, s[76:77]
	s_addc_u32 s11, s11, 0
	s_add_i32 s0, s12, s20
	global_load_lds_dwordx4 v[84:85], off
	v_lshl_add_u64 v[84:85], s[10:11], 0, v[50:51]
	s_mov_b32 m0, s0
	s_nop 0
	global_load_lds_dwordx4 v[84:85], off
	v_lshl_add_u64 v[84:85], s[10:11], 0, v[46:47]
	s_add_i32 m0, s0, 0x2000
	s_nop 0
	global_load_lds_dwordx4 v[84:85], off
	v_lshl_add_u64 v[84:85], v[152:153], 0, s[76:77]
	s_mov_b32 m0, s37
	s_nop 0
	global_load_lds_dwordx4 v[84:85], off
	v_lshl_add_u64 v[84:85], v[154:155], 0, s[76:77]
	s_mov_b32 m0, s38
	s_nop 0
	global_load_lds_dwordx4 v[84:85], off
	s_waitcnt vmcnt(8)
	s_waitcnt lgkmcnt(0)
	s_barrier
	s_barrier
	s_add_i32 s27, s27, 2
	s_add_u32 s8, s8, 0x100
	s_addc_u32 s9, s9, 0
	s_cmp_gt_u32 s27, 13
	s_cbranch_scc0 .LBB0_268
	s_cmpk_lt_u32 s15, 0x100
	s_cbranch_scc0 .LBB0_271
	s_barrier

.LBB0_282:
	s_ashr_i32 s59, s58, 31
	s_lshl_b64 s[20:21], s[58:59], 19
	s_add_u32 s64, s26, s20
	s_addc_u32 s65, s27, s21
	s_and_b64 s[20:21], s[8:9], exec
	s_cselect_b32 s20, s65, s5
	s_cselect_b32 s21, s64, s4
	s_ashr_i32 s57, s56, 31
	s_lshl_b64 s[36:37], s[56:57], 19
	s_add_u32 s66, s35, s36
	s_addc_u32 s67, s40, s37
	s_and_b64 s[36:37], s[8:9], exec
	s_cselect_b32 s36, s67, s7
	s_cselect_b32 s37, s66, s6
	s_add_u32 s4, s4, 0x40080
	s_addc_u32 s5, s5, 0
	s_add_u32 s46, s6, 0x100
	s_addc_u32 s57, s7, 0
	s_mov_b32 s59, -2
	s_add_u32 s6, s4, 0xfffc0080
	s_addc_u32 s7, s5, -1
	s_add_i32 s82, 0, 0x10000
	s_cmp_eq_u32 s59, 12
	s_cselect_b32 s69, s20, s7
	s_cselect_b32 s68, s21, s6
	s_cselect_b32 s7, s36, s57
	s_cselect_b32 s6, s37, s46
	s_add_i32 s84, 0, 0x14000
	v_add_u32_e32 v142, s82, v202
	v_add_u32_e32 v158, s84, v202
	ds_read_b128 v[130:133], v142
	ds_read_b128 v[134:137], v142 offset:1024
	ds_read_b128 v[138:141], v142 offset:2048
	ds_read_b128 v[142:145], v142 offset:3072
	ds_read_b128 v[146:149], v158
	ds_read_b128 v[150:153], v158 offset:1024
	ds_read_b128 v[154:157], v158 offset:2048
	ds_read_b128 v[158:161], v158 offset:3072
	v_lshl_add_u64 v[218:219], s[4:5], 0, v[182:183]
	s_add_i32 m0, s87, 0xc000
	ds_read_b128 v[186:189], v204
	ds_read_b128 v[190:193], v204 offset:1024
	ds_read_b128 v[194:197], v204 offset:2048
	ds_read_b128 v[198:201], v204 offset:3072
	ds_read_b128 v[206:209], v204 offset:4096
	ds_read_b128 v[210:213], v204 offset:5120
	ds_read_b128 v[214:217], v204 offset:6144
	ds_read_b128 v[238:241], v204 offset:7168
	global_load_lds_dwordx4 v[218:219], off
	v_lshl_add_u64 v[218:219], s[4:5], 0, v[184:185]
	s_add_i32 m0, s87, 0xe000
	s_nop 0
	global_load_lds_dwordx4 v[218:219], off
	s_waitcnt vmcnt(8)
	s_waitcnt lgkmcnt(0)
	s_barrier
	s_waitcnt lgkmcnt(0)
	v_mfma_f32_16x16x32_bf16 v[2:5], v[130:133], v[186:189], 0
	v_mfma_f32_16x16x32_bf16 v[6:9], v[138:141], v[186:189], 0
	v_mfma_f32_16x16x32_bf16 v[30:33], v[130:133], v[194:197], 0
	v_mfma_f32_16x16x32_bf16 v[26:29], v[138:141], v[194:197], 0
	v_mfma_f32_16x16x32_bf16 v[34:37], v[130:133], v[206:209], 0
	v_mfma_f32_16x16x32_bf16 v[42:45], v[138:141], v[206:209], 0
	v_mfma_f32_16x16x32_bf16 v[62:65], v[130:133], v[214:217], 0
	v_mfma_f32_16x16x32_bf16 v[58:61], v[138:141], v[214:217], 0
	v_mfma_f32_16x16x32_bf16 v[2:5], v[134:137], v[190:193], v[2:5]
	v_mfma_f32_16x16x32_bf16 v[6:9], v[142:145], v[190:193], v[6:9]
	v_mfma_f32_16x16x32_bf16 v[30:33], v[134:137], v[198:201], v[30:33]
	v_mfma_f32_16x16x32_bf16 v[26:29], v[142:145], v[198:201], v[26:29]
	v_mfma_f32_16x16x32_bf16 v[34:37], v[134:137], v[210:213], v[34:37]
	v_mfma_f32_16x16x32_bf16 v[42:45], v[142:145], v[210:213], v[42:45]
	v_mfma_f32_16x16x32_bf16 v[62:65], v[134:137], v[238:241], v[62:65]
	v_mfma_f32_16x16x32_bf16 v[58:61], v[142:145], v[238:241], v[58:61]
	v_mfma_f32_16x16x32_bf16 v[14:17], v[146:149], v[186:189], 0
	v_mfma_f32_16x16x32_bf16 v[10:13], v[154:157], v[186:189], 0
	v_mfma_f32_16x16x32_bf16 v[22:25], v[146:149], v[194:197], 0
	v_mfma_f32_16x16x32_bf16 v[18:21], v[154:157], v[194:197], 0
	v_mfma_f32_16x16x32_bf16 v[46:49], v[146:149], v[206:209], 0
	v_mfma_f32_16x16x32_bf16 v[38:41], v[154:157], v[206:209], 0
	v_mfma_f32_16x16x32_bf16 v[54:57], v[146:149], v[214:217], 0
	v_mfma_f32_16x16x32_bf16 v[50:53], v[154:157], v[214:217], 0
	v_mfma_f32_16x16x32_bf16 v[14:17], v[150:153], v[190:193], v[14:17]
	v_mfma_f32_16x16x32_bf16 v[10:13], v[158:161], v[190:193], v[10:13]
	v_mfma_f32_16x16x32_bf16 v[22:25], v[150:153], v[198:201], v[22:25]
	v_mfma_f32_16x16x32_bf16 v[18:21], v[158:161], v[198:201], v[18:21]
	v_mfma_f32_16x16x32_bf16 v[46:49], v[150:153], v[210:213], v[46:49]
	v_mfma_f32_16x16x32_bf16 v[38:41], v[158:161], v[210:213], v[38:41]
	v_mfma_f32_16x16x32_bf16 v[54:57], v[150:153], v[238:241], v[54:57]
	v_mfma_f32_16x16x32_bf16 v[50:53], v[158:161], v[238:241], v[50:53]
	s_barrier
	s_add_i32 s82, s82, s41
	v_lshl_add_u64 v[218:219], s[6:7], 0, v[164:165]
	s_mov_b32 m0, s82
	ds_read_b128 v[186:189], v204 offset:16384
	ds_read_b128 v[190:193], v204 offset:17408
	ds_read_b128 v[194:197], v204 offset:18432
	ds_read_b128 v[198:201], v204 offset:19456
	ds_read_b128 v[206:209], v204 offset:20480
	ds_read_b128 v[210:213], v204 offset:21504
	ds_read_b128 v[214:217], v204 offset:22528
	ds_read_b128 v[238:241], v204 offset:23552
	global_load_lds_dwordx4 v[218:219], off
	s_add_i32 m0, s82, 0x2000
	s_add_u32 s82, s6, 0x40000
	v_lshl_add_u64 v[230:231], s[6:7], 0, v[162:163]
	s_addc_u32 s83, s7, 0
	s_add_i32 s84, s84, s41
	global_load_lds_dwordx4 v[230:231], off
	v_lshl_add_u64 v[232:233], s[82:83], 0, v[164:165]
	s_mov_b32 m0, s84
	v_lshl_add_u64 v[242:243], s[68:69], 0, v[162:163]
	global_load_lds_dwordx4 v[232:233], off
	v_lshl_add_u64 v[232:233], s[82:83], 0, v[162:163]
	s_add_i32 m0, s84, 0x2000
	s_nop 0
	global_load_lds_dwordx4 v[232:233], off
	v_lshl_add_u64 v[232:233], s[68:69], 0, v[164:165]
	s_mov_b32 m0, s87
	s_nop 0
	global_load_lds_dwordx4 v[232:233], off
	s_mov_b32 m0, s75
	s_nop 0
	global_load_lds_dwordx4 v[242:243], off
	s_waitcnt vmcnt(8)
	s_waitcnt lgkmcnt(0)
	s_barrier
	s_waitcnt lgkmcnt(0)
	v_mfma_f32_16x16x32_bf16 v[74:77], v[130:133], v[186:189], 0
	v_mfma_f32_16x16x32_bf16 v[70:73], v[138:141], v[186:189], 0
	v_mfma_f32_16x16x32_bf16 v[94:97], v[130:133], v[194:197], 0
	v_mfma_f32_16x16x32_bf16 v[90:93], v[138:141], v[194:197], 0
	v_mfma_f32_16x16x32_bf16 v[106:109], v[130:133], v[206:209], 0
	v_mfma_f32_16x16x32_bf16 v[102:105], v[138:141], v[206:209], 0
	v_mfma_f32_16x16x32_bf16 v[118:121], v[130:133], v[214:217], 0
	v_mfma_f32_16x16x32_bf16 v[114:117], v[138:141], v[214:217], 0
	v_mfma_f32_16x16x32_bf16 v[74:77], v[134:137], v[190:193], v[74:77]
	v_mfma_f32_16x16x32_bf16 v[70:73], v[142:145], v[190:193], v[70:73]
	v_mfma_f32_16x16x32_bf16 v[94:97], v[134:137], v[198:201], v[94:97]
	v_mfma_f32_16x16x32_bf16 v[90:93], v[142:145], v[198:201], v[90:93]
	v_mfma_f32_16x16x32_bf16 v[106:109], v[134:137], v[210:213], v[106:109]
	v_mfma_f32_16x16x32_bf16 v[102:105], v[142:145], v[210:213], v[102:105]
	v_mfma_f32_16x16x32_bf16 v[118:121], v[134:137], v[238:241], v[118:121]
	v_mfma_f32_16x16x32_bf16 v[114:117], v[142:145], v[238:241], v[114:117]
	v_mfma_f32_16x16x32_bf16 v[78:81], v[146:149], v[186:189], 0
	v_mfma_f32_16x16x32_bf16 v[66:69], v[154:157], v[186:189], 0
	v_mfma_f32_16x16x32_bf16 v[86:89], v[146:149], v[194:197], 0
	v_mfma_f32_16x16x32_bf16 v[82:85], v[154:157], v[194:197], 0
	v_mfma_f32_16x16x32_bf16 v[110:113], v[146:149], v[206:209], 0
	v_mfma_f32_16x16x32_bf16 v[98:101], v[154:157], v[206:209], 0
	v_mfma_f32_16x16x32_bf16 v[122:125], v[146:149], v[214:217], 0
	v_mfma_f32_16x16x32_bf16 v[126:129], v[154:157], v[214:217], 0
	v_mfma_f32_16x16x32_bf16 v[78:81], v[150:153], v[190:193], v[78:81]
	v_mfma_f32_16x16x32_bf16 v[66:69], v[158:161], v[190:193], v[66:69]
	v_mfma_f32_16x16x32_bf16 v[86:89], v[150:153], v[198:201], v[86:89]
	v_mfma_f32_16x16x32_bf16 v[82:85], v[158:161], v[198:201], v[82:85]
	v_mfma_f32_16x16x32_bf16 v[110:113], v[150:153], v[210:213], v[110:113]
	v_mfma_f32_16x16x32_bf16 v[98:101], v[158:161], v[210:213], v[98:101]
	v_mfma_f32_16x16x32_bf16 v[122:125], v[150:153], v[238:241], v[122:125]
	v_mfma_f32_16x16x32_bf16 v[126:129], v[158:161], v[238:241], v[126:129]
	s_barrier
	s_add_i32 s82, 0, 0x18000
	s_add_i32 s83, 0, 0x1c000
	v_add_u32_e32 v142, s82, v202
	v_add_u32_e32 v158, s83, v202
	ds_read_b128 v[130:133], v142
	ds_read_b128 v[134:137], v142 offset:1024
	ds_read_b128 v[138:141], v142 offset:2048
	ds_read_b128 v[142:145], v142 offset:3072
	ds_read_b128 v[146:149], v158
	ds_read_b128 v[150:153], v158 offset:1024
	ds_read_b128 v[154:157], v158 offset:2048
	ds_read_b128 v[158:161], v158 offset:3072
	s_add_u32 s68, s68, 0x40000
	s_addc_u32 s69, s69, 0
	s_mov_b32 m0, s72
	v_lshl_add_u64 v[244:245], s[68:69], 0, v[164:165]
	ds_read_b128 v[186:189], v204 offset:32768
	ds_read_b128 v[190:193], v204 offset:33792
	ds_read_b128 v[194:197], v204 offset:34816
	ds_read_b128 v[198:201], v204 offset:35840
	ds_read_b128 v[206:209], v204 offset:36864
	ds_read_b128 v[210:213], v204 offset:37888
	ds_read_b128 v[214:217], v204 offset:38912
	ds_read_b128 v[238:241], v204 offset:39936
	global_load_lds_dwordx4 v[244:245], off
	v_lshl_add_u64 v[244:245], s[68:69], 0, v[162:163]
	s_mov_b32 m0, s73
	s_nop 0
	global_load_lds_dwordx4 v[244:245], off
	s_waitcnt vmcnt(8)
	s_waitcnt lgkmcnt(0)
	s_barrier
	s_waitcnt lgkmcnt(0)
	v_mfma_f32_16x16x32_bf16 v[2:5], v[130:133], v[186:189], v[2:5]
	v_mfma_f32_16x16x32_bf16 v[6:9], v[138:141], v[186:189], v[6:9]
	v_mfma_f32_16x16x32_bf16 v[30:33], v[130:133], v[194:197], v[30:33]
	v_mfma_f32_16x16x32_bf16 v[26:29], v[138:141], v[194:197], v[26:29]
	v_mfma_f32_16x16x32_bf16 v[34:37], v[130:133], v[206:209], v[34:37]
	v_mfma_f32_16x16x32_bf16 v[42:45], v[138:141], v[206:209], v[42:45]
	v_mfma_f32_16x16x32_bf16 v[62:65], v[130:133], v[214:217], v[62:65]
	v_mfma_f32_16x16x32_bf16 v[58:61], v[138:141], v[214:217], v[58:61]
	v_mfma_f32_16x16x32_bf16 v[2:5], v[134:137], v[190:193], v[2:5]
	v_mfma_f32_16x16x32_bf16 v[6:9], v[142:145], v[190:193], v[6:9]
	v_mfma_f32_16x16x32_bf16 v[30:33], v[134:137], v[198:201], v[30:33]
	v_mfma_f32_16x16x32_bf16 v[26:29], v[142:145], v[198:201], v[26:29]
	v_mfma_f32_16x16x32_bf16 v[34:37], v[134:137], v[210:213], v[34:37]
	v_mfma_f32_16x16x32_bf16 v[42:45], v[142:145], v[210:213], v[42:45]
	v_mfma_f32_16x16x32_bf16 v[62:65], v[134:137], v[238:241], v[62:65]
	v_mfma_f32_16x16x32_bf16 v[58:61], v[142:145], v[238:241], v[58:61]
	v_mfma_f32_16x16x32_bf16 v[14:17], v[146:149], v[186:189], v[14:17]
	v_mfma_f32_16x16x32_bf16 v[10:13], v[154:157], v[186:189], v[10:13]
	v_mfma_f32_16x16x32_bf16 v[22:25], v[146:149], v[194:197], v[22:25]
	v_mfma_f32_16x16x32_bf16 v[18:21], v[154:157], v[194:197], v[18:21]
	v_mfma_f32_16x16x32_bf16 v[46:49], v[146:149], v[206:209], v[46:49]
	v_mfma_f32_16x16x32_bf16 v[38:41], v[154:157], v[206:209], v[38:41]
	v_mfma_f32_16x16x32_bf16 v[54:57], v[146:149], v[214:217], v[54:57]
	v_mfma_f32_16x16x32_bf16 v[50:53], v[154:157], v[214:217], v[50:53]
	v_mfma_f32_16x16x32_bf16 v[14:17], v[150:153], v[190:193], v[14:17]
	v_mfma_f32_16x16x32_bf16 v[10:13], v[158:161], v[190:193], v[10:13]
	v_mfma_f32_16x16x32_bf16 v[22:25], v[150:153], v[198:201], v[22:25]
	v_mfma_f32_16x16x32_bf16 v[18:21], v[158:161], v[198:201], v[18:21]
	v_mfma_f32_16x16x32_bf16 v[46:49], v[150:153], v[210:213], v[46:49]
	v_mfma_f32_16x16x32_bf16 v[38:41], v[158:161], v[210:213], v[38:41]
	v_mfma_f32_16x16x32_bf16 v[54:57], v[150:153], v[238:241], v[54:57]
	v_mfma_f32_16x16x32_bf16 v[50:53], v[158:161], v[238:241], v[50:53]
	s_barrier
	s_add_i32 s68, s82, s41
	v_lshl_add_u64 v[218:219], v[218:219], 0, s[76:77]
	s_mov_b32 m0, s68
	ds_read_b128 v[186:189], v204 offset:49152
	ds_read_b128 v[190:193], v204 offset:50176
	ds_read_b128 v[194:197], v204 offset:51200
	ds_read_b128 v[198:201], v204 offset:52224
	ds_read_b128 v[206:209], v204 offset:53248
	ds_read_b128 v[210:213], v204 offset:54272
	ds_read_b128 v[214:217], v204 offset:55296
	ds_read_b128 v[238:241], v204 offset:56320
	global_load_lds_dwordx4 v[218:219], off
	s_add_i32 m0, s68, 0x2000
	s_add_u32 s6, s6, 0x40080
	v_lshl_add_u64 v[218:219], v[230:231], 0, s[76:77]
	s_addc_u32 s7, s7, 0
	s_add_i32 s68, s83, s41
	global_load_lds_dwordx4 v[218:219], off
	v_lshl_add_u64 v[218:219], s[6:7], 0, v[164:165]
	s_mov_b32 m0, s68
	s_nop 0
	global_load_lds_dwordx4 v[218:219], off
	v_lshl_add_u64 v[218:219], s[6:7], 0, v[162:163]
	s_add_i32 m0, s68, 0x2000
	s_nop 0
	global_load_lds_dwordx4 v[218:219], off
	v_lshl_add_u64 v[218:219], v[232:233], 0, s[76:77]
	s_mov_b32 m0, s34
	s_nop 0
	global_load_lds_dwordx4 v[218:219], off
	v_lshl_add_u64 v[218:219], v[242:243], 0, s[76:77]
	s_mov_b32 m0, s30
	s_nop 0
	global_load_lds_dwordx4 v[218:219], off
	s_waitcnt vmcnt(8)
	s_waitcnt lgkmcnt(0)
	s_barrier
	s_waitcnt lgkmcnt(0)
	v_mfma_f32_16x16x32_bf16 v[74:77], v[130:133], v[186:189], v[74:77]
	v_mfma_f32_16x16x32_bf16 v[70:73], v[138:141], v[186:189], v[70:73]
	v_mfma_f32_16x16x32_bf16 v[94:97], v[130:133], v[194:197], v[94:97]
	v_mfma_f32_16x16x32_bf16 v[90:93], v[138:141], v[194:197], v[90:93]
	v_mfma_f32_16x16x32_bf16 v[106:109], v[130:133], v[206:209], v[106:109]
	v_mfma_f32_16x16x32_bf16 v[102:105], v[138:141], v[206:209], v[102:105]
	v_mfma_f32_16x16x32_bf16 v[118:121], v[130:133], v[214:217], v[118:121]
	v_mfma_f32_16x16x32_bf16 v[114:117], v[138:141], v[214:217], v[114:117]
	v_mfma_f32_16x16x32_bf16 v[74:77], v[134:137], v[190:193], v[74:77]
	v_mfma_f32_16x16x32_bf16 v[70:73], v[142:145], v[190:193], v[70:73]
	v_mfma_f32_16x16x32_bf16 v[94:97], v[134:137], v[198:201], v[94:97]
	v_mfma_f32_16x16x32_bf16 v[90:93], v[142:145], v[198:201], v[90:93]
	v_mfma_f32_16x16x32_bf16 v[106:109], v[134:137], v[210:213], v[106:109]
	v_mfma_f32_16x16x32_bf16 v[102:105], v[142:145], v[210:213], v[102:105]
	v_mfma_f32_16x16x32_bf16 v[118:121], v[134:137], v[238:241], v[118:121]
	v_mfma_f32_16x16x32_bf16 v[114:117], v[142:145], v[238:241], v[114:117]
	v_mfma_f32_16x16x32_bf16 v[78:81], v[146:149], v[186:189], v[78:81]
	v_mfma_f32_16x16x32_bf16 v[66:69], v[154:157], v[186:189], v[66:69]
	v_mfma_f32_16x16x32_bf16 v[86:89], v[146:149], v[194:197], v[86:89]
	v_mfma_f32_16x16x32_bf16 v[82:85], v[154:157], v[194:197], v[82:85]
	v_mfma_f32_16x16x32_bf16 v[110:113], v[146:149], v[206:209], v[110:113]
	v_mfma_f32_16x16x32_bf16 v[98:101], v[154:157], v[206:209], v[98:101]
	v_mfma_f32_16x16x32_bf16 v[122:125], v[146:149], v[214:217], v[122:125]
	v_mfma_f32_16x16x32_bf16 v[126:129], v[154:157], v[214:217], v[126:129]
	v_mfma_f32_16x16x32_bf16 v[78:81], v[150:153], v[190:193], v[78:81]
	v_mfma_f32_16x16x32_bf16 v[66:69], v[158:161], v[190:193], v[66:69]
	v_mfma_f32_16x16x32_bf16 v[86:89], v[150:153], v[198:201], v[86:89]
	v_mfma_f32_16x16x32_bf16 v[82:85], v[158:161], v[198:201], v[82:85]
	v_mfma_f32_16x16x32_bf16 v[110:113], v[150:153], v[210:213], v[110:113]
	v_mfma_f32_16x16x32_bf16 v[98:101], v[158:161], v[210:213], v[98:101]
	v_mfma_f32_16x16x32_bf16 v[122:125], v[150:153], v[238:241], v[122:125]
	v_mfma_f32_16x16x32_bf16 v[126:129], v[158:161], v[238:241], v[126:129]
	s_barrier
	s_add_i32 s59, s59, 2
	s_add_u32 s4, s4, 0x100
	s_addc_u32 s5, s5, 0
	s_add_u32 s46, s46, 0x100
	s_addc_u32 s57, s57, 0
.LBB0_283:
	s_add_u32 s6, s4, 0xfffc0080
	s_addc_u32 s7, s5, -1
	s_add_i32 s82, 0, 0x10000
	s_cmp_eq_u32 s59, 12
	s_cselect_b32 s69, s20, s7
	s_cselect_b32 s68, s21, s6
	s_cselect_b32 s7, s36, s57
	s_cselect_b32 s6, s37, s46
	s_add_i32 s84, 0, 0x14000
	v_add_u32_e32 v142, s82, v202
	v_add_u32_e32 v158, s84, v202
	ds_read_b128 v[130:133], v142
	ds_read_b128 v[134:137], v142 offset:1024
	ds_read_b128 v[138:141], v142 offset:2048
	ds_read_b128 v[142:145], v142 offset:3072
	ds_read_b128 v[146:149], v158
	ds_read_b128 v[150:153], v158 offset:1024
	ds_read_b128 v[154:157], v158 offset:2048
	ds_read_b128 v[158:161], v158 offset:3072
	v_lshl_add_u64 v[218:219], s[4:5], 0, v[182:183]
	s_add_i32 m0, s87, 0xc000
	ds_read_b128 v[186:189], v204
	ds_read_b128 v[190:193], v204 offset:1024
	ds_read_b128 v[194:197], v204 offset:2048
	ds_read_b128 v[198:201], v204 offset:3072
	ds_read_b128 v[206:209], v204 offset:4096
	ds_read_b128 v[210:213], v204 offset:5120
	ds_read_b128 v[214:217], v204 offset:6144
	ds_read_b128 v[238:241], v204 offset:7168
	global_load_lds_dwordx4 v[218:219], off
	v_lshl_add_u64 v[218:219], s[4:5], 0, v[184:185]
	s_add_i32 m0, s87, 0xe000
	s_nop 0
	global_load_lds_dwordx4 v[218:219], off
	s_waitcnt vmcnt(8)
	s_waitcnt lgkmcnt(0)
	s_barrier
	s_waitcnt lgkmcnt(0)
	v_mfma_f32_16x16x32_bf16 v[2:5], v[130:133], v[186:189], v[2:5]
	v_mfma_f32_16x16x32_bf16 v[6:9], v[138:141], v[186:189], v[6:9]
	v_mfma_f32_16x16x32_bf16 v[30:33], v[130:133], v[194:197], v[30:33]
	v_mfma_f32_16x16x32_bf16 v[26:29], v[138:141], v[194:197], v[26:29]
	v_mfma_f32_16x16x32_bf16 v[34:37], v[130:133], v[206:209], v[34:37]
	v_mfma_f32_16x16x32_bf16 v[42:45], v[138:141], v[206:209], v[42:45]
	v_mfma_f32_16x16x32_bf16 v[62:65], v[130:133], v[214:217], v[62:65]
	v_mfma_f32_16x16x32_bf16 v[58:61], v[138:141], v[214:217], v[58:61]
	v_mfma_f32_16x16x32_bf16 v[2:5], v[134:137], v[190:193], v[2:5]
	v_mfma_f32_16x16x32_bf16 v[6:9], v[142:145], v[190:193], v[6:9]
	v_mfma_f32_16x16x32_bf16 v[30:33], v[134:137], v[198:201], v[30:33]
	v_mfma_f32_16x16x32_bf16 v[26:29], v[142:145], v[198:201], v[26:29]
	v_mfma_f32_16x16x32_bf16 v[34:37], v[134:137], v[210:213], v[34:37]
	v_mfma_f32_16x16x32_bf16 v[42:45], v[142:145], v[210:213], v[42:45]
	v_mfma_f32_16x16x32_bf16 v[62:65], v[134:137], v[238:241], v[62:65]
	v_mfma_f32_16x16x32_bf16 v[58:61], v[142:145], v[238:241], v[58:61]
	v_mfma_f32_16x16x32_bf16 v[14:17], v[146:149], v[186:189], v[14:17]
	v_mfma_f32_16x16x32_bf16 v[10:13], v[154:157], v[186:189], v[10:13]
	v_mfma_f32_16x16x32_bf16 v[22:25], v[146:149], v[194:197], v[22:25]
	v_mfma_f32_16x16x32_bf16 v[18:21], v[154:157], v[194:197], v[18:21]
	v_mfma_f32_16x16x32_bf16 v[46:49], v[146:149], v[206:209], v[46:49]
	v_mfma_f32_16x16x32_bf16 v[38:41], v[154:157], v[206:209], v[38:41]
	v_mfma_f32_16x16x32_bf16 v[54:57], v[146:149], v[214:217], v[54:57]
	v_mfma_f32_16x16x32_bf16 v[50:53], v[154:157], v[214:217], v[50:53]
	v_mfma_f32_16x16x32_bf16 v[14:17], v[150:153], v[190:193], v[14:17]
	v_mfma_f32_16x16x32_bf16 v[10:13], v[158:161], v[190:193], v[10:13]
	v_mfma_f32_16x16x32_bf16 v[22:25], v[150:153], v[198:201], v[22:25]
	v_mfma_f32_16x16x32_bf16 v[18:21], v[158:161], v[198:201], v[18:21]
	v_mfma_f32_16x16x32_bf16 v[46:49], v[150:153], v[210:213], v[46:49]
	v_mfma_f32_16x16x32_bf16 v[38:41], v[158:161], v[210:213], v[38:41]
	v_mfma_f32_16x16x32_bf16 v[54:57], v[150:153], v[238:241], v[54:57]
	v_mfma_f32_16x16x32_bf16 v[50:53], v[158:161], v[238:241], v[50:53]
	s_barrier
	s_add_i32 s82, s82, s41
	v_lshl_add_u64 v[218:219], s[6:7], 0, v[164:165]
	s_mov_b32 m0, s82
	ds_read_b128 v[186:189], v204 offset:16384
	ds_read_b128 v[190:193], v204 offset:17408
	ds_read_b128 v[194:197], v204 offset:18432
	ds_read_b128 v[198:201], v204 offset:19456
	ds_read_b128 v[206:209], v204 offset:20480
	ds_read_b128 v[210:213], v204 offset:21504
	ds_read_b128 v[214:217], v204 offset:22528
	ds_read_b128 v[238:241], v204 offset:23552
	global_load_lds_dwordx4 v[218:219], off
	s_add_i32 m0, s82, 0x2000
	s_add_u32 s82, s6, 0x40000
	v_lshl_add_u64 v[230:231], s[6:7], 0, v[162:163]
	s_addc_u32 s83, s7, 0
	s_add_i32 s84, s84, s41
	global_load_lds_dwordx4 v[230:231], off
	v_lshl_add_u64 v[232:233], s[82:83], 0, v[164:165]
	s_mov_b32 m0, s84
	v_lshl_add_u64 v[242:243], s[68:69], 0, v[162:163]
	global_load_lds_dwordx4 v[232:233], off
	v_lshl_add_u64 v[232:233], s[82:83], 0, v[162:163]
	s_add_i32 m0, s84, 0x2000
	s_nop 0
	global_load_lds_dwordx4 v[232:233], off
	v_lshl_add_u64 v[232:233], s[68:69], 0, v[164:165]
	s_mov_b32 m0, s87
	s_nop 0
	global_load_lds_dwordx4 v[232:233], off
	s_mov_b32 m0, s75
	s_nop 0
	global_load_lds_dwordx4 v[242:243], off
	s_waitcnt vmcnt(8)
	s_waitcnt lgkmcnt(0)
	s_barrier
	s_waitcnt lgkmcnt(0)
	v_mfma_f32_16x16x32_bf16 v[74:77], v[130:133], v[186:189], v[74:77]
	v_mfma_f32_16x16x32_bf16 v[70:73], v[138:141], v[186:189], v[70:73]
	v_mfma_f32_16x16x32_bf16 v[94:97], v[130:133], v[194:197], v[94:97]
	v_mfma_f32_16x16x32_bf16 v[90:93], v[138:141], v[194:197], v[90:93]
	v_mfma_f32_16x16x32_bf16 v[106:109], v[130:133], v[206:209], v[106:109]
	v_mfma_f32_16x16x32_bf16 v[102:105], v[138:141], v[206:209], v[102:105]
	v_mfma_f32_16x16x32_bf16 v[118:121], v[130:133], v[214:217], v[118:121]
	v_mfma_f32_16x16x32_bf16 v[114:117], v[138:141], v[214:217], v[114:117]
	v_mfma_f32_16x16x32_bf16 v[74:77], v[134:137], v[190:193], v[74:77]
	v_mfma_f32_16x16x32_bf16 v[70:73], v[142:145], v[190:193], v[70:73]
	v_mfma_f32_16x16x32_bf16 v[94:97], v[134:137], v[198:201], v[94:97]
	v_mfma_f32_16x16x32_bf16 v[90:93], v[142:145], v[198:201], v[90:93]
	v_mfma_f32_16x16x32_bf16 v[106:109], v[134:137], v[210:213], v[106:109]
	v_mfma_f32_16x16x32_bf16 v[102:105], v[142:145], v[210:213], v[102:105]
	v_mfma_f32_16x16x32_bf16 v[118:121], v[134:137], v[238:241], v[118:121]
	v_mfma_f32_16x16x32_bf16 v[114:117], v[142:145], v[238:241], v[114:117]
	v_mfma_f32_16x16x32_bf16 v[78:81], v[146:149], v[186:189], v[78:81]
	v_mfma_f32_16x16x32_bf16 v[66:69], v[154:157], v[186:189], v[66:69]
	v_mfma_f32_16x16x32_bf16 v[86:89], v[146:149], v[194:197], v[86:89]
	v_mfma_f32_16x16x32_bf16 v[82:85], v[154:157], v[194:197], v[82:85]
	v_mfma_f32_16x16x32_bf16 v[110:113], v[146:149], v[206:209], v[110:113]
	v_mfma_f32_16x16x32_bf16 v[98:101], v[154:157], v[206:209], v[98:101]
	v_mfma_f32_16x16x32_bf16 v[122:125], v[146:149], v[214:217], v[122:125]
	v_mfma_f32_16x16x32_bf16 v[126:129], v[154:157], v[214:217], v[126:129]
	v_mfma_f32_16x16x32_bf16 v[78:81], v[150:153], v[190:193], v[78:81]
	v_mfma_f32_16x16x32_bf16 v[66:69], v[158:161], v[190:193], v[66:69]
	v_mfma_f32_16x16x32_bf16 v[86:89], v[150:153], v[198:201], v[86:89]
	v_mfma_f32_16x16x32_bf16 v[82:85], v[158:161], v[198:201], v[82:85]
	v_mfma_f32_16x16x32_bf16 v[110:113], v[150:153], v[210:213], v[110:113]
	v_mfma_f32_16x16x32_bf16 v[98:101], v[158:161], v[210:213], v[98:101]
	v_mfma_f32_16x16x32_bf16 v[122:125], v[150:153], v[238:241], v[122:125]
	v_mfma_f32_16x16x32_bf16 v[126:129], v[158:161], v[238:241], v[126:129]
	s_barrier
	s_add_i32 s82, 0, 0x18000
	s_add_i32 s83, 0, 0x1c000
	v_add_u32_e32 v142, s82, v202
	v_add_u32_e32 v158, s83, v202
	ds_read_b128 v[130:133], v142
	ds_read_b128 v[134:137], v142 offset:1024
	ds_read_b128 v[138:141], v142 offset:2048
	ds_read_b128 v[142:145], v142 offset:3072
	ds_read_b128 v[146:149], v158
	ds_read_b128 v[150:153], v158 offset:1024
	ds_read_b128 v[154:157], v158 offset:2048
	ds_read_b128 v[158:161], v158 offset:3072
	s_add_u32 s68, s68, 0x40000
	s_addc_u32 s69, s69, 0
	s_mov_b32 m0, s72
	v_lshl_add_u64 v[244:245], s[68:69], 0, v[164:165]
	ds_read_b128 v[186:189], v204 offset:32768
	ds_read_b128 v[190:193], v204 offset:33792
	ds_read_b128 v[194:197], v204 offset:34816
	ds_read_b128 v[198:201], v204 offset:35840
	ds_read_b128 v[206:209], v204 offset:36864
	ds_read_b128 v[210:213], v204 offset:37888
	ds_read_b128 v[214:217], v204 offset:38912
	ds_read_b128 v[238:241], v204 offset:39936
	global_load_lds_dwordx4 v[244:245], off
	v_lshl_add_u64 v[244:245], s[68:69], 0, v[162:163]
	s_mov_b32 m0, s73
	s_nop 0
	global_load_lds_dwordx4 v[244:245], off
	s_waitcnt vmcnt(8)
	s_waitcnt lgkmcnt(0)
	s_barrier
	s_waitcnt lgkmcnt(0)
	v_mfma_f32_16x16x32_bf16 v[2:5], v[130:133], v[186:189], v[2:5]
	v_mfma_f32_16x16x32_bf16 v[6:9], v[138:141], v[186:189], v[6:9]
	v_mfma_f32_16x16x32_bf16 v[30:33], v[130:133], v[194:197], v[30:33]
	v_mfma_f32_16x16x32_bf16 v[26:29], v[138:141], v[194:197], v[26:29]
	v_mfma_f32_16x16x32_bf16 v[34:37], v[130:133], v[206:209], v[34:37]
	v_mfma_f32_16x16x32_bf16 v[42:45], v[138:141], v[206:209], v[42:45]
	v_mfma_f32_16x16x32_bf16 v[62:65], v[130:133], v[214:217], v[62:65]
	v_mfma_f32_16x16x32_bf16 v[58:61], v[138:141], v[214:217], v[58:61]
	v_mfma_f32_16x16x32_bf16 v[2:5], v[134:137], v[190:193], v[2:5]
	v_mfma_f32_16x16x32_bf16 v[6:9], v[142:145], v[190:193], v[6:9]
	v_mfma_f32_16x16x32_bf16 v[30:33], v[134:137], v[198:201], v[30:33]
	v_mfma_f32_16x16x32_bf16 v[26:29], v[142:145], v[198:201], v[26:29]
	v_mfma_f32_16x16x32_bf16 v[34:37], v[134:137], v[210:213], v[34:37]
	v_mfma_f32_16x16x32_bf16 v[42:45], v[142:145], v[210:213], v[42:45]
	v_mfma_f32_16x16x32_bf16 v[62:65], v[134:137], v[238:241], v[62:65]
	v_mfma_f32_16x16x32_bf16 v[58:61], v[142:145], v[238:241], v[58:61]
	v_mfma_f32_16x16x32_bf16 v[14:17], v[146:149], v[186:189], v[14:17]
	v_mfma_f32_16x16x32_bf16 v[10:13], v[154:157], v[186:189], v[10:13]
	v_mfma_f32_16x16x32_bf16 v[22:25], v[146:149], v[194:197], v[22:25]
	v_mfma_f32_16x16x32_bf16 v[18:21], v[154:157], v[194:197], v[18:21]
	v_mfma_f32_16x16x32_bf16 v[46:49], v[146:149], v[206:209], v[46:49]
	v_mfma_f32_16x16x32_bf16 v[38:41], v[154:157], v[206:209], v[38:41]
	v_mfma_f32_16x16x32_bf16 v[54:57], v[146:149], v[214:217], v[54:57]
	v_mfma_f32_16x16x32_bf16 v[50:53], v[154:157], v[214:217], v[50:53]
	v_mfma_f32_16x16x32_bf16 v[14:17], v[150:153], v[190:193], v[14:17]
	v_mfma_f32_16x16x32_bf16 v[10:13], v[158:161], v[190:193], v[10:13]
	v_mfma_f32_16x16x32_bf16 v[22:25], v[150:153], v[198:201], v[22:25]
	v_mfma_f32_16x16x32_bf16 v[18:21], v[158:161], v[198:201], v[18:21]
	v_mfma_f32_16x16x32_bf16 v[46:49], v[150:153], v[210:213], v[46:49]
	v_mfma_f32_16x16x32_bf16 v[38:41], v[158:161], v[210:213], v[38:41]
	v_mfma_f32_16x16x32_bf16 v[54:57], v[150:153], v[238:241], v[54:57]
	v_mfma_f32_16x16x32_bf16 v[50:53], v[158:161], v[238:241], v[50:53]
	s_barrier
	s_add_i32 s68, s82, s41
	v_lshl_add_u64 v[218:219], v[218:219], 0, s[76:77]
	s_mov_b32 m0, s68
	ds_read_b128 v[186:189], v204 offset:49152
	ds_read_b128 v[190:193], v204 offset:50176
	ds_read_b128 v[194:197], v204 offset:51200
	ds_read_b128 v[198:201], v204 offset:52224
	ds_read_b128 v[206:209], v204 offset:53248
	ds_read_b128 v[210:213], v204 offset:54272
	ds_read_b128 v[214:217], v204 offset:55296
	ds_read_b128 v[238:241], v204 offset:56320
	global_load_lds_dwordx4 v[218:219], off
	s_add_i32 m0, s68, 0x2000
	s_add_u32 s6, s6, 0x40080
	v_lshl_add_u64 v[218:219], v[230:231], 0, s[76:77]
	s_addc_u32 s7, s7, 0
	s_add_i32 s68, s83, s41
	global_load_lds_dwordx4 v[218:219], off
	v_lshl_add_u64 v[218:219], s[6:7], 0, v[164:165]
	s_mov_b32 m0, s68
	s_nop 0
	global_load_lds_dwordx4 v[218:219], off
	v_lshl_add_u64 v[218:219], s[6:7], 0, v[162:163]
	s_add_i32 m0, s68, 0x2000
	s_nop 0
	global_load_lds_dwordx4 v[218:219], off
	v_lshl_add_u64 v[218:219], v[232:233], 0, s[76:77]
	s_mov_b32 m0, s34
	s_nop 0
	global_load_lds_dwordx4 v[218:219], off
	v_lshl_add_u64 v[218:219], v[242:243], 0, s[76:77]
	s_mov_b32 m0, s30
	s_nop 0
	global_load_lds_dwordx4 v[218:219], off
	s_waitcnt vmcnt(8)
	s_waitcnt lgkmcnt(0)
	s_barrier
	s_waitcnt lgkmcnt(0)
	v_mfma_f32_16x16x32_bf16 v[74:77], v[130:133], v[186:189], v[74:77]
	v_mfma_f32_16x16x32_bf16 v[70:73], v[138:141], v[186:189], v[70:73]
	v_mfma_f32_16x16x32_bf16 v[94:97], v[130:133], v[194:197], v[94:97]
	v_mfma_f32_16x16x32_bf16 v[90:93], v[138:141], v[194:197], v[90:93]
	v_mfma_f32_16x16x32_bf16 v[106:109], v[130:133], v[206:209], v[106:109]
	v_mfma_f32_16x16x32_bf16 v[102:105], v[138:141], v[206:209], v[102:105]
	v_mfma_f32_16x16x32_bf16 v[118:121], v[130:133], v[214:217], v[118:121]
	v_mfma_f32_16x16x32_bf16 v[114:117], v[138:141], v[214:217], v[114:117]
	v_mfma_f32_16x16x32_bf16 v[74:77], v[134:137], v[190:193], v[74:77]
	v_mfma_f32_16x16x32_bf16 v[70:73], v[142:145], v[190:193], v[70:73]
	v_mfma_f32_16x16x32_bf16 v[94:97], v[134:137], v[198:201], v[94:97]
	v_mfma_f32_16x16x32_bf16 v[90:93], v[142:145], v[198:201], v[90:93]
	v_mfma_f32_16x16x32_bf16 v[106:109], v[134:137], v[210:213], v[106:109]
	v_mfma_f32_16x16x32_bf16 v[102:105], v[142:145], v[210:213], v[102:105]
	v_mfma_f32_16x16x32_bf16 v[118:121], v[134:137], v[238:241], v[118:121]
	v_mfma_f32_16x16x32_bf16 v[114:117], v[142:145], v[238:241], v[114:117]
	v_mfma_f32_16x16x32_bf16 v[78:81], v[146:149], v[186:189], v[78:81]
	v_mfma_f32_16x16x32_bf16 v[66:69], v[154:157], v[186:189], v[66:69]
	v_mfma_f32_16x16x32_bf16 v[86:89], v[146:149], v[194:197], v[86:89]
	v_mfma_f32_16x16x32_bf16 v[82:85], v[154:157], v[194:197], v[82:85]
	v_mfma_f32_16x16x32_bf16 v[110:113], v[146:149], v[206:209], v[110:113]
	v_mfma_f32_16x16x32_bf16 v[98:101], v[154:157], v[206:209], v[98:101]
	v_mfma_f32_16x16x32_bf16 v[122:125], v[146:149], v[214:217], v[122:125]
	v_mfma_f32_16x16x32_bf16 v[126:129], v[154:157], v[214:217], v[126:129]
	v_mfma_f32_16x16x32_bf16 v[78:81], v[150:153], v[190:193], v[78:81]
	v_mfma_f32_16x16x32_bf16 v[66:69], v[158:161], v[190:193], v[66:69]
	v_mfma_f32_16x16x32_bf16 v[86:89], v[150:153], v[198:201], v[86:89]
	v_mfma_f32_16x16x32_bf16 v[82:85], v[158:161], v[198:201], v[82:85]
	v_mfma_f32_16x16x32_bf16 v[110:113], v[150:153], v[210:213], v[110:113]
	v_mfma_f32_16x16x32_bf16 v[98:101], v[158:161], v[210:213], v[98:101]
	v_mfma_f32_16x16x32_bf16 v[122:125], v[150:153], v[238:241], v[122:125]
	v_mfma_f32_16x16x32_bf16 v[126:129], v[158:161], v[238:241], v[126:129]
	s_barrier
	s_add_i32 s59, s59, 2
	s_add_u32 s4, s4, 0x100
	s_addc_u32 s5, s5, 0
	s_add_u32 s46, s46, 0x100
	s_addc_u32 s57, s57, 0
	s_cmp_gt_u32 s59, 13
	s_cbranch_scc0 .LBB0_283
	s_and_b64 vcc, exec, s[42:43]
	s_cbranch_vccz .LBB0_286
	s_barrier

.LBB0_670:
	s_add_u32 s6, s58, 0x80
	s_addc_u32 s7, s59, 0
	s_add_u32 s21, s56, 0x100
	s_addc_u32 s26, s57, 0
	s_mov_b32 s27, 0
	s_add_i32 s46, s27, 2
	s_add_u32 s0, s6, 0x80
	s_addc_u32 s56, s7, 0
	s_add_i32 vcc_lo, 0, 0x10000
	s_cmp_eq_u32 s72, s27
	s_cselect_b32 s57, s51, s56
	s_cselect_b32 s56, s50, s0
	s_cselect_b32 s59, s53, s26
	s_cselect_b32 s58, s52, s21
	s_add_i32 s0, 0, 0x14000
	v_add_u32_e32 v70, vcc_lo, v237
	v_add_u32_e32 v94, s0, v237
	ds_read_b128 v[58:61], v70
	ds_read_b128 v[62:65], v70 offset:1024
	ds_read_b128 v[66:69], v70 offset:2048
	ds_read_b128 v[70:73], v70 offset:3072
	ds_read_b128 v[82:85], v94
	ds_read_b128 v[86:89], v94 offset:1024
	ds_read_b128 v[90:93], v94 offset:2048
	ds_read_b128 v[94:97], v94 offset:3072
	v_lshl_add_u64 v[210:211], s[6:7], 0, v[194:195]
	s_add_i32 m0, s64, 0xc000
	ds_read_b128 v[162:165], v239
	ds_read_b128 v[166:169], v239 offset:1024
	ds_read_b128 v[170:173], v239 offset:2048
	ds_read_b128 v[174:177], v239 offset:3072
	ds_read_b128 v[178:181], v239 offset:4096
	ds_read_b128 v[198:201], v239 offset:5120
	ds_read_b128 v[202:205], v239 offset:6144
	ds_read_b128 v[206:209], v239 offset:7168
	global_load_lds_dwordx4 v[210:211], off
	v_lshl_add_u64 v[210:211], s[6:7], 0, v[196:197]
	s_add_i32 m0, s64, 0xe000
	s_nop 0
	global_load_lds_dwordx4 v[210:211], off
	s_waitcnt vmcnt(8)
	s_waitcnt lgkmcnt(0)
	s_barrier
	s_waitcnt lgkmcnt(0)
	v_mfma_f32_16x16x32_bf16 v[158:161], v[58:61], v[162:165], 0
	v_mfma_f32_16x16x32_bf16 v[154:157], v[66:69], v[162:165], 0
	v_mfma_f32_16x16x32_bf16 v[142:145], v[58:61], v[170:173], 0
	v_mfma_f32_16x16x32_bf16 v[138:141], v[66:69], v[170:173], 0
	v_mfma_f32_16x16x32_bf16 v[126:129], v[58:61], v[178:181], 0
	v_mfma_f32_16x16x32_bf16 v[122:125], v[66:69], v[178:181], 0
	v_mfma_f32_16x16x32_bf16 v[110:113], v[58:61], v[202:205], 0
	v_mfma_f32_16x16x32_bf16 v[106:109], v[66:69], v[202:205], 0
	v_mfma_f32_16x16x32_bf16 v[158:161], v[62:65], v[166:169], v[158:161]
	v_mfma_f32_16x16x32_bf16 v[154:157], v[70:73], v[166:169], v[154:157]
	v_mfma_f32_16x16x32_bf16 v[142:145], v[62:65], v[174:177], v[142:145]
	v_mfma_f32_16x16x32_bf16 v[138:141], v[70:73], v[174:177], v[138:141]
	v_mfma_f32_16x16x32_bf16 v[126:129], v[62:65], v[198:201], v[126:129]
	v_mfma_f32_16x16x32_bf16 v[122:125], v[70:73], v[198:201], v[122:125]
	v_mfma_f32_16x16x32_bf16 v[110:113], v[62:65], v[206:209], v[110:113]
	v_mfma_f32_16x16x32_bf16 v[106:109], v[70:73], v[206:209], v[106:109]
	v_mfma_f32_16x16x32_bf16 v[150:153], v[82:85], v[162:165], 0
	v_mfma_f32_16x16x32_bf16 v[146:149], v[90:93], v[162:165], 0
	v_mfma_f32_16x16x32_bf16 v[134:137], v[82:85], v[170:173], 0
	v_mfma_f32_16x16x32_bf16 v[130:133], v[90:93], v[170:173], 0
	v_mfma_f32_16x16x32_bf16 v[118:121], v[82:85], v[178:181], 0
	v_mfma_f32_16x16x32_bf16 v[114:117], v[90:93], v[178:181], 0
	v_mfma_f32_16x16x32_bf16 v[102:105], v[82:85], v[202:205], 0
	v_mfma_f32_16x16x32_bf16 v[98:101], v[90:93], v[202:205], 0
	v_mfma_f32_16x16x32_bf16 v[150:153], v[86:89], v[166:169], v[150:153]
	v_mfma_f32_16x16x32_bf16 v[146:149], v[94:97], v[166:169], v[146:149]
	v_mfma_f32_16x16x32_bf16 v[134:137], v[86:89], v[174:177], v[134:137]
	v_mfma_f32_16x16x32_bf16 v[130:133], v[94:97], v[174:177], v[130:133]
	v_mfma_f32_16x16x32_bf16 v[118:121], v[86:89], v[198:201], v[118:121]
	v_mfma_f32_16x16x32_bf16 v[114:117], v[94:97], v[198:201], v[114:117]
	v_mfma_f32_16x16x32_bf16 v[102:105], v[86:89], v[206:209], v[102:105]
	v_mfma_f32_16x16x32_bf16 v[98:101], v[94:97], v[206:209], v[98:101]
	s_barrier
	s_add_i32 s27, vcc_lo, s61
	v_lshl_add_u64 v[210:211], s[58:59], 0, v[186:187]
	s_mov_b32 m0, s27
	ds_read_b128 v[162:165], v239 offset:16384
	ds_read_b128 v[166:169], v239 offset:17408
	ds_read_b128 v[170:173], v239 offset:18432
	ds_read_b128 v[174:177], v239 offset:19456
	ds_read_b128 v[178:181], v239 offset:20480
	ds_read_b128 v[198:201], v239 offset:21504
	ds_read_b128 v[202:205], v239 offset:22528
	ds_read_b128 v[206:209], v239 offset:23552
	global_load_lds_dwordx4 v[210:211], off
	s_add_i32 m0, s27, 0x2000
	v_lshl_add_u64 v[212:213], s[58:59], 0, v[182:183]
	s_add_u32 s58, s58, s12
	s_addc_u32 s59, s59, 0
	s_add_i32 s0, s0, s61
	global_load_lds_dwordx4 v[212:213], off
	v_lshl_add_u64 v[214:215], s[58:59], 0, v[186:187]
	s_mov_b32 m0, s0
	v_lshl_add_u64 v[216:217], s[58:59], 0, v[182:183]
	global_load_lds_dwordx4 v[214:215], off
	s_add_i32 m0, s0, 0x2000
	v_lshl_add_u64 v[218:219], s[56:57], 0, v[188:189]
	global_load_lds_dwordx4 v[216:217], off
	s_mov_b32 m0, s64
	v_lshl_add_u64 v[230:231], s[56:57], 0, v[184:185]
	global_load_lds_dwordx4 v[218:219], off
	s_mov_b32 m0, s65
	s_nop 0
	global_load_lds_dwordx4 v[230:231], off
	s_waitcnt vmcnt(8)
	s_waitcnt lgkmcnt(0)
	s_barrier
	s_waitcnt lgkmcnt(0)
	v_mfma_f32_16x16x32_bf16 v[78:81], v[58:61], v[162:165], 0
	v_mfma_f32_16x16x32_bf16 v[74:77], v[66:69], v[162:165], 0
	v_mfma_f32_16x16x32_bf16 v[46:49], v[58:61], v[170:173], 0
	v_mfma_f32_16x16x32_bf16 v[42:45], v[66:69], v[170:173], 0
	v_mfma_f32_16x16x32_bf16 v[30:33], v[58:61], v[178:181], 0
	v_mfma_f32_16x16x32_bf16 v[26:29], v[66:69], v[178:181], 0
	v_mfma_f32_16x16x32_bf16 v[14:17], v[58:61], v[202:205], 0
	v_mfma_f32_16x16x32_bf16 v[10:13], v[66:69], v[202:205], 0
	v_mfma_f32_16x16x32_bf16 v[78:81], v[62:65], v[166:169], v[78:81]
	v_mfma_f32_16x16x32_bf16 v[74:77], v[70:73], v[166:169], v[74:77]
	v_mfma_f32_16x16x32_bf16 v[46:49], v[62:65], v[174:177], v[46:49]
	v_mfma_f32_16x16x32_bf16 v[42:45], v[70:73], v[174:177], v[42:45]
	v_mfma_f32_16x16x32_bf16 v[30:33], v[62:65], v[198:201], v[30:33]
	v_mfma_f32_16x16x32_bf16 v[26:29], v[70:73], v[198:201], v[26:29]
	v_mfma_f32_16x16x32_bf16 v[14:17], v[62:65], v[206:209], v[14:17]
	v_mfma_f32_16x16x32_bf16 v[10:13], v[70:73], v[206:209], v[10:13]
	v_mfma_f32_16x16x32_bf16 v[54:57], v[82:85], v[162:165], 0
	v_mfma_f32_16x16x32_bf16 v[50:53], v[90:93], v[162:165], 0
	v_mfma_f32_16x16x32_bf16 v[38:41], v[82:85], v[170:173], 0
	v_mfma_f32_16x16x32_bf16 v[34:37], v[90:93], v[170:173], 0
	v_mfma_f32_16x16x32_bf16 v[22:25], v[82:85], v[178:181], 0
	v_mfma_f32_16x16x32_bf16 v[18:21], v[90:93], v[178:181], 0
	v_mfma_f32_16x16x32_bf16 v[6:9], v[82:85], v[202:205], 0
	v_mfma_f32_16x16x32_bf16 v[2:5], v[90:93], v[202:205], 0
	v_mfma_f32_16x16x32_bf16 v[54:57], v[86:89], v[166:169], v[54:57]
	v_mfma_f32_16x16x32_bf16 v[50:53], v[94:97], v[166:169], v[50:53]
	v_mfma_f32_16x16x32_bf16 v[38:41], v[86:89], v[174:177], v[38:41]
	v_mfma_f32_16x16x32_bf16 v[34:37], v[94:97], v[174:177], v[34:37]
	v_mfma_f32_16x16x32_bf16 v[22:25], v[86:89], v[198:201], v[22:25]
	v_mfma_f32_16x16x32_bf16 v[18:21], v[94:97], v[198:201], v[18:21]
	v_mfma_f32_16x16x32_bf16 v[6:9], v[86:89], v[206:209], v[6:9]
	v_mfma_f32_16x16x32_bf16 v[2:5], v[94:97], v[206:209], v[2:5]
	s_barrier
	s_add_i32 s0, 0, 0x18000
	s_add_i32 s27, 0, 0x1c000
	v_add_u32_e32 v70, s0, v237
	v_add_u32_e32 v94, s27, v237
	ds_read_b128 v[58:61], v70
	ds_read_b128 v[62:65], v70 offset:1024
	ds_read_b128 v[66:69], v70 offset:2048
	ds_read_b128 v[70:73], v70 offset:3072
	ds_read_b128 v[82:85], v94
	ds_read_b128 v[86:89], v94 offset:1024
	ds_read_b128 v[90:93], v94 offset:2048
	ds_read_b128 v[94:97], v94 offset:3072
	s_add_u32 s56, s56, s12
	s_addc_u32 s57, s57, 0
	s_mov_b32 m0, s66
	v_lshl_add_u64 v[232:233], s[56:57], 0, v[188:189]
	ds_read_b128 v[162:165], v239 offset:32768
	ds_read_b128 v[166:169], v239 offset:33792
	ds_read_b128 v[170:173], v239 offset:34816
	ds_read_b128 v[174:177], v239 offset:35840
	ds_read_b128 v[178:181], v239 offset:36864
	ds_read_b128 v[198:201], v239 offset:37888
	ds_read_b128 v[202:205], v239 offset:38912
	ds_read_b128 v[206:209], v239 offset:39936
	global_load_lds_dwordx4 v[232:233], off
	v_lshl_add_u64 v[232:233], s[56:57], 0, v[184:185]
	s_mov_b32 m0, s67
	s_nop 0
	global_load_lds_dwordx4 v[232:233], off
	s_waitcnt vmcnt(8)
	s_waitcnt lgkmcnt(0)
	s_barrier
	s_waitcnt lgkmcnt(0)
	v_mfma_f32_16x16x32_bf16 v[158:161], v[58:61], v[162:165], v[158:161]
	v_mfma_f32_16x16x32_bf16 v[154:157], v[66:69], v[162:165], v[154:157]
	v_mfma_f32_16x16x32_bf16 v[142:145], v[58:61], v[170:173], v[142:145]
	v_mfma_f32_16x16x32_bf16 v[138:141], v[66:69], v[170:173], v[138:141]
	v_mfma_f32_16x16x32_bf16 v[126:129], v[58:61], v[178:181], v[126:129]
	v_mfma_f32_16x16x32_bf16 v[122:125], v[66:69], v[178:181], v[122:125]
	v_mfma_f32_16x16x32_bf16 v[110:113], v[58:61], v[202:205], v[110:113]
	v_mfma_f32_16x16x32_bf16 v[106:109], v[66:69], v[202:205], v[106:109]
	v_mfma_f32_16x16x32_bf16 v[158:161], v[62:65], v[166:169], v[158:161]
	v_mfma_f32_16x16x32_bf16 v[154:157], v[70:73], v[166:169], v[154:157]
	v_mfma_f32_16x16x32_bf16 v[142:145], v[62:65], v[174:177], v[142:145]
	v_mfma_f32_16x16x32_bf16 v[138:141], v[70:73], v[174:177], v[138:141]
	v_mfma_f32_16x16x32_bf16 v[126:129], v[62:65], v[198:201], v[126:129]
	v_mfma_f32_16x16x32_bf16 v[122:125], v[70:73], v[198:201], v[122:125]
	v_mfma_f32_16x16x32_bf16 v[110:113], v[62:65], v[206:209], v[110:113]
	v_mfma_f32_16x16x32_bf16 v[106:109], v[70:73], v[206:209], v[106:109]
	v_mfma_f32_16x16x32_bf16 v[150:153], v[82:85], v[162:165], v[150:153]
	v_mfma_f32_16x16x32_bf16 v[146:149], v[90:93], v[162:165], v[146:149]
	v_mfma_f32_16x16x32_bf16 v[134:137], v[82:85], v[170:173], v[134:137]
	v_mfma_f32_16x16x32_bf16 v[130:133], v[90:93], v[170:173], v[130:133]
	v_mfma_f32_16x16x32_bf16 v[118:121], v[82:85], v[178:181], v[118:121]
	v_mfma_f32_16x16x32_bf16 v[114:117], v[90:93], v[178:181], v[114:117]
	v_mfma_f32_16x16x32_bf16 v[102:105], v[82:85], v[202:205], v[102:105]
	v_mfma_f32_16x16x32_bf16 v[98:101], v[90:93], v[202:205], v[98:101]
	v_mfma_f32_16x16x32_bf16 v[150:153], v[86:89], v[166:169], v[150:153]
	v_mfma_f32_16x16x32_bf16 v[146:149], v[94:97], v[166:169], v[146:149]
	v_mfma_f32_16x16x32_bf16 v[134:137], v[86:89], v[174:177], v[134:137]
	v_mfma_f32_16x16x32_bf16 v[130:133], v[94:97], v[174:177], v[130:133]
	v_mfma_f32_16x16x32_bf16 v[118:121], v[86:89], v[198:201], v[118:121]
	v_mfma_f32_16x16x32_bf16 v[114:117], v[94:97], v[198:201], v[114:117]
	v_mfma_f32_16x16x32_bf16 v[102:105], v[86:89], v[206:209], v[102:105]
	v_mfma_f32_16x16x32_bf16 v[98:101], v[94:97], v[206:209], v[98:101]
	s_barrier
	s_add_i32 s0, s0, s61
	v_lshl_add_u64 v[210:211], v[210:211], 0, s[76:77]
	s_mov_b32 m0, s0
	ds_read_b128 v[162:165], v239 offset:49152
	ds_read_b128 v[166:169], v239 offset:50176
	ds_read_b128 v[170:173], v239 offset:51200
	ds_read_b128 v[174:177], v239 offset:52224
	ds_read_b128 v[178:181], v239 offset:53248
	ds_read_b128 v[198:201], v239 offset:54272
	ds_read_b128 v[202:205], v239 offset:55296
	ds_read_b128 v[206:209], v239 offset:56320
	global_load_lds_dwordx4 v[210:211], off
	v_lshl_add_u64 v[210:211], v[212:213], 0, s[76:77]
	s_add_i32 m0, s0, 0x2000
	s_add_i32 s0, s27, s61
	global_load_lds_dwordx4 v[210:211], off
	v_lshl_add_u64 v[210:211], v[214:215], 0, s[76:77]
	s_mov_b32 m0, s0
	s_nop 0
	global_load_lds_dwordx4 v[210:211], off
	v_lshl_add_u64 v[210:211], v[216:217], 0, s[76:77]
	s_add_i32 m0, s0, 0x2000
	s_nop 0
	global_load_lds_dwordx4 v[210:211], off
	v_lshl_add_u64 v[210:211], v[218:219], 0, s[76:77]
	s_mov_b32 m0, s68
	s_nop 0
	global_load_lds_dwordx4 v[210:211], off
	v_lshl_add_u64 v[210:211], v[230:231], 0, s[76:77]
	s_mov_b32 m0, s69
	s_nop 0
	global_load_lds_dwordx4 v[210:211], off
	s_waitcnt vmcnt(8)
	s_waitcnt lgkmcnt(0)
	s_barrier
	s_waitcnt lgkmcnt(0)
	v_mfma_f32_16x16x32_bf16 v[78:81], v[58:61], v[162:165], v[78:81]
	v_mfma_f32_16x16x32_bf16 v[74:77], v[66:69], v[162:165], v[74:77]
	v_mfma_f32_16x16x32_bf16 v[46:49], v[58:61], v[170:173], v[46:49]
	v_mfma_f32_16x16x32_bf16 v[42:45], v[66:69], v[170:173], v[42:45]
	v_mfma_f32_16x16x32_bf16 v[30:33], v[58:61], v[178:181], v[30:33]
	v_mfma_f32_16x16x32_bf16 v[26:29], v[66:69], v[178:181], v[26:29]
	v_mfma_f32_16x16x32_bf16 v[14:17], v[58:61], v[202:205], v[14:17]
	v_mfma_f32_16x16x32_bf16 v[10:13], v[66:69], v[202:205], v[10:13]
	v_mfma_f32_16x16x32_bf16 v[78:81], v[62:65], v[166:169], v[78:81]
	v_mfma_f32_16x16x32_bf16 v[74:77], v[70:73], v[166:169], v[74:77]
	v_mfma_f32_16x16x32_bf16 v[46:49], v[62:65], v[174:177], v[46:49]
	v_mfma_f32_16x16x32_bf16 v[42:45], v[70:73], v[174:177], v[42:45]
	v_mfma_f32_16x16x32_bf16 v[30:33], v[62:65], v[198:201], v[30:33]
	v_mfma_f32_16x16x32_bf16 v[26:29], v[70:73], v[198:201], v[26:29]
	v_mfma_f32_16x16x32_bf16 v[14:17], v[62:65], v[206:209], v[14:17]
	v_mfma_f32_16x16x32_bf16 v[10:13], v[70:73], v[206:209], v[10:13]
	v_mfma_f32_16x16x32_bf16 v[54:57], v[82:85], v[162:165], v[54:57]
	v_mfma_f32_16x16x32_bf16 v[50:53], v[90:93], v[162:165], v[50:53]
	v_mfma_f32_16x16x32_bf16 v[38:41], v[82:85], v[170:173], v[38:41]
	v_mfma_f32_16x16x32_bf16 v[34:37], v[90:93], v[170:173], v[34:37]
	v_mfma_f32_16x16x32_bf16 v[22:25], v[82:85], v[178:181], v[22:25]
	v_mfma_f32_16x16x32_bf16 v[18:21], v[90:93], v[178:181], v[18:21]
	v_mfma_f32_16x16x32_bf16 v[6:9], v[82:85], v[202:205], v[6:9]
	v_mfma_f32_16x16x32_bf16 v[2:5], v[90:93], v[202:205], v[2:5]
	v_mfma_f32_16x16x32_bf16 v[54:57], v[86:89], v[166:169], v[54:57]
	v_mfma_f32_16x16x32_bf16 v[50:53], v[94:97], v[166:169], v[50:53]
	v_mfma_f32_16x16x32_bf16 v[38:41], v[86:89], v[174:177], v[38:41]
	v_mfma_f32_16x16x32_bf16 v[34:37], v[94:97], v[174:177], v[34:37]
	v_mfma_f32_16x16x32_bf16 v[22:25], v[86:89], v[198:201], v[22:25]
	v_mfma_f32_16x16x32_bf16 v[18:21], v[94:97], v[198:201], v[18:21]
	v_mfma_f32_16x16x32_bf16 v[6:9], v[86:89], v[206:209], v[6:9]
	v_mfma_f32_16x16x32_bf16 v[2:5], v[94:97], v[206:209], v[2:5]
	s_barrier
	s_add_u32 s6, s6, 0x100
	s_addc_u32 s7, s7, 0
	s_add_u32 s21, s21, 0x100
	s_addc_u32 s26, s26, 0
	s_mov_b32 s27, s46
.LBB0_671:
	s_add_i32 s46, s27, 2
	s_add_u32 s0, s6, 0x80
	s_addc_u32 s56, s7, 0
	s_add_i32 vcc_lo, 0, 0x10000
	s_cmp_eq_u32 s72, s27
	s_cselect_b32 s57, s51, s56
	s_cselect_b32 s56, s50, s0
	s_cselect_b32 s59, s53, s26
	s_cselect_b32 s58, s52, s21
	s_add_i32 s0, 0, 0x14000
	v_add_u32_e32 v70, vcc_lo, v237
	v_add_u32_e32 v94, s0, v237
	ds_read_b128 v[58:61], v70
	ds_read_b128 v[62:65], v70 offset:1024
	ds_read_b128 v[66:69], v70 offset:2048
	ds_read_b128 v[70:73], v70 offset:3072
	ds_read_b128 v[82:85], v94
	ds_read_b128 v[86:89], v94 offset:1024
	ds_read_b128 v[90:93], v94 offset:2048
	ds_read_b128 v[94:97], v94 offset:3072
	v_lshl_add_u64 v[210:211], s[6:7], 0, v[194:195]
	s_add_i32 m0, s64, 0xc000
	ds_read_b128 v[162:165], v239
	ds_read_b128 v[166:169], v239 offset:1024
	ds_read_b128 v[170:173], v239 offset:2048
	ds_read_b128 v[174:177], v239 offset:3072
	ds_read_b128 v[178:181], v239 offset:4096
	ds_read_b128 v[198:201], v239 offset:5120
	ds_read_b128 v[202:205], v239 offset:6144
	ds_read_b128 v[206:209], v239 offset:7168
	global_load_lds_dwordx4 v[210:211], off
	v_lshl_add_u64 v[210:211], s[6:7], 0, v[196:197]
	s_add_i32 m0, s64, 0xe000
	s_nop 0
	global_load_lds_dwordx4 v[210:211], off
	s_waitcnt vmcnt(8)
	s_waitcnt lgkmcnt(0)
	s_barrier
	s_waitcnt lgkmcnt(0)
	v_mfma_f32_16x16x32_bf16 v[158:161], v[58:61], v[162:165], v[158:161]
	v_mfma_f32_16x16x32_bf16 v[154:157], v[66:69], v[162:165], v[154:157]
	v_mfma_f32_16x16x32_bf16 v[142:145], v[58:61], v[170:173], v[142:145]
	v_mfma_f32_16x16x32_bf16 v[138:141], v[66:69], v[170:173], v[138:141]
	v_mfma_f32_16x16x32_bf16 v[126:129], v[58:61], v[178:181], v[126:129]
	v_mfma_f32_16x16x32_bf16 v[122:125], v[66:69], v[178:181], v[122:125]
	v_mfma_f32_16x16x32_bf16 v[110:113], v[58:61], v[202:205], v[110:113]
	v_mfma_f32_16x16x32_bf16 v[106:109], v[66:69], v[202:205], v[106:109]
	v_mfma_f32_16x16x32_bf16 v[158:161], v[62:65], v[166:169], v[158:161]
	v_mfma_f32_16x16x32_bf16 v[154:157], v[70:73], v[166:169], v[154:157]
	v_mfma_f32_16x16x32_bf16 v[142:145], v[62:65], v[174:177], v[142:145]
	v_mfma_f32_16x16x32_bf16 v[138:141], v[70:73], v[174:177], v[138:141]
	v_mfma_f32_16x16x32_bf16 v[126:129], v[62:65], v[198:201], v[126:129]
	v_mfma_f32_16x16x32_bf16 v[122:125], v[70:73], v[198:201], v[122:125]
	v_mfma_f32_16x16x32_bf16 v[110:113], v[62:65], v[206:209], v[110:113]
	v_mfma_f32_16x16x32_bf16 v[106:109], v[70:73], v[206:209], v[106:109]
	v_mfma_f32_16x16x32_bf16 v[150:153], v[82:85], v[162:165], v[150:153]
	v_mfma_f32_16x16x32_bf16 v[146:149], v[90:93], v[162:165], v[146:149]
	v_mfma_f32_16x16x32_bf16 v[134:137], v[82:85], v[170:173], v[134:137]
	v_mfma_f32_16x16x32_bf16 v[130:133], v[90:93], v[170:173], v[130:133]
	v_mfma_f32_16x16x32_bf16 v[118:121], v[82:85], v[178:181], v[118:121]
	v_mfma_f32_16x16x32_bf16 v[114:117], v[90:93], v[178:181], v[114:117]
	v_mfma_f32_16x16x32_bf16 v[102:105], v[82:85], v[202:205], v[102:105]
	v_mfma_f32_16x16x32_bf16 v[98:101], v[90:93], v[202:205], v[98:101]
	v_mfma_f32_16x16x32_bf16 v[150:153], v[86:89], v[166:169], v[150:153]
	v_mfma_f32_16x16x32_bf16 v[146:149], v[94:97], v[166:169], v[146:149]
	v_mfma_f32_16x16x32_bf16 v[134:137], v[86:89], v[174:177], v[134:137]
	v_mfma_f32_16x16x32_bf16 v[130:133], v[94:97], v[174:177], v[130:133]
	v_mfma_f32_16x16x32_bf16 v[118:121], v[86:89], v[198:201], v[118:121]
	v_mfma_f32_16x16x32_bf16 v[114:117], v[94:97], v[198:201], v[114:117]
	v_mfma_f32_16x16x32_bf16 v[102:105], v[86:89], v[206:209], v[102:105]
	v_mfma_f32_16x16x32_bf16 v[98:101], v[94:97], v[206:209], v[98:101]
	s_barrier
	s_add_i32 s27, vcc_lo, s61
	v_lshl_add_u64 v[210:211], s[58:59], 0, v[186:187]
	s_mov_b32 m0, s27
	ds_read_b128 v[162:165], v239 offset:16384
	ds_read_b128 v[166:169], v239 offset:17408
	ds_read_b128 v[170:173], v239 offset:18432
	ds_read_b128 v[174:177], v239 offset:19456
	ds_read_b128 v[178:181], v239 offset:20480
	ds_read_b128 v[198:201], v239 offset:21504
	ds_read_b128 v[202:205], v239 offset:22528
	ds_read_b128 v[206:209], v239 offset:23552
	global_load_lds_dwordx4 v[210:211], off
	s_add_i32 m0, s27, 0x2000
	v_lshl_add_u64 v[212:213], s[58:59], 0, v[182:183]
	s_add_u32 s58, s58, s12
	s_addc_u32 s59, s59, 0
	s_add_i32 s0, s0, s61
	global_load_lds_dwordx4 v[212:213], off
	v_lshl_add_u64 v[214:215], s[58:59], 0, v[186:187]
	s_mov_b32 m0, s0
	v_lshl_add_u64 v[216:217], s[58:59], 0, v[182:183]
	global_load_lds_dwordx4 v[214:215], off
	s_add_i32 m0, s0, 0x2000
	v_lshl_add_u64 v[218:219], s[56:57], 0, v[188:189]
	global_load_lds_dwordx4 v[216:217], off
	s_mov_b32 m0, s64
	v_lshl_add_u64 v[230:231], s[56:57], 0, v[184:185]
	global_load_lds_dwordx4 v[218:219], off
	s_mov_b32 m0, s65
	s_nop 0
	global_load_lds_dwordx4 v[230:231], off
	s_waitcnt vmcnt(8)
	s_waitcnt lgkmcnt(0)
	s_barrier
	s_waitcnt lgkmcnt(0)
	v_mfma_f32_16x16x32_bf16 v[78:81], v[58:61], v[162:165], v[78:81]
	v_mfma_f32_16x16x32_bf16 v[74:77], v[66:69], v[162:165], v[74:77]
	v_mfma_f32_16x16x32_bf16 v[46:49], v[58:61], v[170:173], v[46:49]
	v_mfma_f32_16x16x32_bf16 v[42:45], v[66:69], v[170:173], v[42:45]
	v_mfma_f32_16x16x32_bf16 v[30:33], v[58:61], v[178:181], v[30:33]
	v_mfma_f32_16x16x32_bf16 v[26:29], v[66:69], v[178:181], v[26:29]
	v_mfma_f32_16x16x32_bf16 v[14:17], v[58:61], v[202:205], v[14:17]
	v_mfma_f32_16x16x32_bf16 v[10:13], v[66:69], v[202:205], v[10:13]
	v_mfma_f32_16x16x32_bf16 v[78:81], v[62:65], v[166:169], v[78:81]
	v_mfma_f32_16x16x32_bf16 v[74:77], v[70:73], v[166:169], v[74:77]
	v_mfma_f32_16x16x32_bf16 v[46:49], v[62:65], v[174:177], v[46:49]
	v_mfma_f32_16x16x32_bf16 v[42:45], v[70:73], v[174:177], v[42:45]
	v_mfma_f32_16x16x32_bf16 v[30:33], v[62:65], v[198:201], v[30:33]
	v_mfma_f32_16x16x32_bf16 v[26:29], v[70:73], v[198:201], v[26:29]
	v_mfma_f32_16x16x32_bf16 v[14:17], v[62:65], v[206:209], v[14:17]
	v_mfma_f32_16x16x32_bf16 v[10:13], v[70:73], v[206:209], v[10:13]
	v_mfma_f32_16x16x32_bf16 v[54:57], v[82:85], v[162:165], v[54:57]
	v_mfma_f32_16x16x32_bf16 v[50:53], v[90:93], v[162:165], v[50:53]
	v_mfma_f32_16x16x32_bf16 v[38:41], v[82:85], v[170:173], v[38:41]
	v_mfma_f32_16x16x32_bf16 v[34:37], v[90:93], v[170:173], v[34:37]
	v_mfma_f32_16x16x32_bf16 v[22:25], v[82:85], v[178:181], v[22:25]
	v_mfma_f32_16x16x32_bf16 v[18:21], v[90:93], v[178:181], v[18:21]
	v_mfma_f32_16x16x32_bf16 v[6:9], v[82:85], v[202:205], v[6:9]
	v_mfma_f32_16x16x32_bf16 v[2:5], v[90:93], v[202:205], v[2:5]
	v_mfma_f32_16x16x32_bf16 v[54:57], v[86:89], v[166:169], v[54:57]
	v_mfma_f32_16x16x32_bf16 v[50:53], v[94:97], v[166:169], v[50:53]
	v_mfma_f32_16x16x32_bf16 v[38:41], v[86:89], v[174:177], v[38:41]
	v_mfma_f32_16x16x32_bf16 v[34:37], v[94:97], v[174:177], v[34:37]
	v_mfma_f32_16x16x32_bf16 v[22:25], v[86:89], v[198:201], v[22:25]
	v_mfma_f32_16x16x32_bf16 v[18:21], v[94:97], v[198:201], v[18:21]
	v_mfma_f32_16x16x32_bf16 v[6:9], v[86:89], v[206:209], v[6:9]
	v_mfma_f32_16x16x32_bf16 v[2:5], v[94:97], v[206:209], v[2:5]
	s_barrier
	s_add_i32 s0, 0, 0x18000
	s_add_i32 s27, 0, 0x1c000
	v_add_u32_e32 v70, s0, v237
	v_add_u32_e32 v94, s27, v237
	ds_read_b128 v[58:61], v70
	ds_read_b128 v[62:65], v70 offset:1024
	ds_read_b128 v[66:69], v70 offset:2048
	ds_read_b128 v[70:73], v70 offset:3072
	ds_read_b128 v[82:85], v94
	ds_read_b128 v[86:89], v94 offset:1024
	ds_read_b128 v[90:93], v94 offset:2048
	ds_read_b128 v[94:97], v94 offset:3072
	s_add_u32 s56, s56, s12
	s_addc_u32 s57, s57, 0
	s_mov_b32 m0, s66
	v_lshl_add_u64 v[232:233], s[56:57], 0, v[188:189]
	ds_read_b128 v[162:165], v239 offset:32768
	ds_read_b128 v[166:169], v239 offset:33792
	ds_read_b128 v[170:173], v239 offset:34816
	ds_read_b128 v[174:177], v239 offset:35840
	ds_read_b128 v[178:181], v239 offset:36864
	ds_read_b128 v[198:201], v239 offset:37888
	ds_read_b128 v[202:205], v239 offset:38912
	ds_read_b128 v[206:209], v239 offset:39936
	global_load_lds_dwordx4 v[232:233], off
	v_lshl_add_u64 v[232:233], s[56:57], 0, v[184:185]
	s_mov_b32 m0, s67
	s_nop 0
	global_load_lds_dwordx4 v[232:233], off
	s_waitcnt vmcnt(8)
	s_waitcnt lgkmcnt(0)
	s_barrier
	s_waitcnt lgkmcnt(0)
	v_mfma_f32_16x16x32_bf16 v[158:161], v[58:61], v[162:165], v[158:161]
	v_mfma_f32_16x16x32_bf16 v[154:157], v[66:69], v[162:165], v[154:157]
	v_mfma_f32_16x16x32_bf16 v[142:145], v[58:61], v[170:173], v[142:145]
	v_mfma_f32_16x16x32_bf16 v[138:141], v[66:69], v[170:173], v[138:141]
	v_mfma_f32_16x16x32_bf16 v[126:129], v[58:61], v[178:181], v[126:129]
	v_mfma_f32_16x16x32_bf16 v[122:125], v[66:69], v[178:181], v[122:125]
	v_mfma_f32_16x16x32_bf16 v[110:113], v[58:61], v[202:205], v[110:113]
	v_mfma_f32_16x16x32_bf16 v[106:109], v[66:69], v[202:205], v[106:109]
	v_mfma_f32_16x16x32_bf16 v[158:161], v[62:65], v[166:169], v[158:161]
	v_mfma_f32_16x16x32_bf16 v[154:157], v[70:73], v[166:169], v[154:157]
	v_mfma_f32_16x16x32_bf16 v[142:145], v[62:65], v[174:177], v[142:145]
	v_mfma_f32_16x16x32_bf16 v[138:141], v[70:73], v[174:177], v[138:141]
	v_mfma_f32_16x16x32_bf16 v[126:129], v[62:65], v[198:201], v[126:129]
	v_mfma_f32_16x16x32_bf16 v[122:125], v[70:73], v[198:201], v[122:125]
	v_mfma_f32_16x16x32_bf16 v[110:113], v[62:65], v[206:209], v[110:113]
	v_mfma_f32_16x16x32_bf16 v[106:109], v[70:73], v[206:209], v[106:109]
	v_mfma_f32_16x16x32_bf16 v[150:153], v[82:85], v[162:165], v[150:153]
	v_mfma_f32_16x16x32_bf16 v[146:149], v[90:93], v[162:165], v[146:149]
	v_mfma_f32_16x16x32_bf16 v[134:137], v[82:85], v[170:173], v[134:137]
	v_mfma_f32_16x16x32_bf16 v[130:133], v[90:93], v[170:173], v[130:133]
	v_mfma_f32_16x16x32_bf16 v[118:121], v[82:85], v[178:181], v[118:121]
	v_mfma_f32_16x16x32_bf16 v[114:117], v[90:93], v[178:181], v[114:117]
	v_mfma_f32_16x16x32_bf16 v[102:105], v[82:85], v[202:205], v[102:105]
	v_mfma_f32_16x16x32_bf16 v[98:101], v[90:93], v[202:205], v[98:101]
	v_mfma_f32_16x16x32_bf16 v[150:153], v[86:89], v[166:169], v[150:153]
	v_mfma_f32_16x16x32_bf16 v[146:149], v[94:97], v[166:169], v[146:149]
	v_mfma_f32_16x16x32_bf16 v[134:137], v[86:89], v[174:177], v[134:137]
	v_mfma_f32_16x16x32_bf16 v[130:133], v[94:97], v[174:177], v[130:133]
	v_mfma_f32_16x16x32_bf16 v[118:121], v[86:89], v[198:201], v[118:121]
	v_mfma_f32_16x16x32_bf16 v[114:117], v[94:97], v[198:201], v[114:117]
	v_mfma_f32_16x16x32_bf16 v[102:105], v[86:89], v[206:209], v[102:105]
	v_mfma_f32_16x16x32_bf16 v[98:101], v[94:97], v[206:209], v[98:101]
	s_barrier
	s_add_i32 s0, s0, s61
	v_lshl_add_u64 v[210:211], v[210:211], 0, s[76:77]
	s_mov_b32 m0, s0
	ds_read_b128 v[162:165], v239 offset:49152
	ds_read_b128 v[166:169], v239 offset:50176
	ds_read_b128 v[170:173], v239 offset:51200
	ds_read_b128 v[174:177], v239 offset:52224
	ds_read_b128 v[178:181], v239 offset:53248
	ds_read_b128 v[198:201], v239 offset:54272
	ds_read_b128 v[202:205], v239 offset:55296
	ds_read_b128 v[206:209], v239 offset:56320
	global_load_lds_dwordx4 v[210:211], off
	v_lshl_add_u64 v[210:211], v[212:213], 0, s[76:77]
	s_add_i32 m0, s0, 0x2000
	s_add_i32 s0, s27, s61
	global_load_lds_dwordx4 v[210:211], off
	v_lshl_add_u64 v[210:211], v[214:215], 0, s[76:77]
	s_mov_b32 m0, s0
	s_nop 0
	global_load_lds_dwordx4 v[210:211], off
	v_lshl_add_u64 v[210:211], v[216:217], 0, s[76:77]
	s_add_i32 m0, s0, 0x2000
	s_nop 0
	global_load_lds_dwordx4 v[210:211], off
	v_lshl_add_u64 v[210:211], v[218:219], 0, s[76:77]
	s_mov_b32 m0, s68
	s_nop 0
	global_load_lds_dwordx4 v[210:211], off
	v_lshl_add_u64 v[210:211], v[230:231], 0, s[76:77]
	s_mov_b32 m0, s69
	s_nop 0
	global_load_lds_dwordx4 v[210:211], off
	s_waitcnt vmcnt(8)
	s_waitcnt lgkmcnt(0)
	s_barrier
	s_waitcnt lgkmcnt(0)
	v_mfma_f32_16x16x32_bf16 v[78:81], v[58:61], v[162:165], v[78:81]
	v_mfma_f32_16x16x32_bf16 v[74:77], v[66:69], v[162:165], v[74:77]
	v_mfma_f32_16x16x32_bf16 v[46:49], v[58:61], v[170:173], v[46:49]
	v_mfma_f32_16x16x32_bf16 v[42:45], v[66:69], v[170:173], v[42:45]
	v_mfma_f32_16x16x32_bf16 v[30:33], v[58:61], v[178:181], v[30:33]
	v_mfma_f32_16x16x32_bf16 v[26:29], v[66:69], v[178:181], v[26:29]
	v_mfma_f32_16x16x32_bf16 v[14:17], v[58:61], v[202:205], v[14:17]
	v_mfma_f32_16x16x32_bf16 v[10:13], v[66:69], v[202:205], v[10:13]
	v_mfma_f32_16x16x32_bf16 v[78:81], v[62:65], v[166:169], v[78:81]
	v_mfma_f32_16x16x32_bf16 v[74:77], v[70:73], v[166:169], v[74:77]
	v_mfma_f32_16x16x32_bf16 v[46:49], v[62:65], v[174:177], v[46:49]
	v_mfma_f32_16x16x32_bf16 v[42:45], v[70:73], v[174:177], v[42:45]
	v_mfma_f32_16x16x32_bf16 v[30:33], v[62:65], v[198:201], v[30:33]
	v_mfma_f32_16x16x32_bf16 v[26:29], v[70:73], v[198:201], v[26:29]
	v_mfma_f32_16x16x32_bf16 v[14:17], v[62:65], v[206:209], v[14:17]
	v_mfma_f32_16x16x32_bf16 v[10:13], v[70:73], v[206:209], v[10:13]
	v_mfma_f32_16x16x32_bf16 v[54:57], v[82:85], v[162:165], v[54:57]
	v_mfma_f32_16x16x32_bf16 v[50:53], v[90:93], v[162:165], v[50:53]
	v_mfma_f32_16x16x32_bf16 v[38:41], v[82:85], v[170:173], v[38:41]
	v_mfma_f32_16x16x32_bf16 v[34:37], v[90:93], v[170:173], v[34:37]
	v_mfma_f32_16x16x32_bf16 v[22:25], v[82:85], v[178:181], v[22:25]
	v_mfma_f32_16x16x32_bf16 v[18:21], v[90:93], v[178:181], v[18:21]
	v_mfma_f32_16x16x32_bf16 v[6:9], v[82:85], v[202:205], v[6:9]
	v_mfma_f32_16x16x32_bf16 v[2:5], v[90:93], v[202:205], v[2:5]
	v_mfma_f32_16x16x32_bf16 v[54:57], v[86:89], v[166:169], v[54:57]
	v_mfma_f32_16x16x32_bf16 v[50:53], v[94:97], v[166:169], v[50:53]
	v_mfma_f32_16x16x32_bf16 v[38:41], v[86:89], v[174:177], v[38:41]
	v_mfma_f32_16x16x32_bf16 v[34:37], v[94:97], v[174:177], v[34:37]
	v_mfma_f32_16x16x32_bf16 v[22:25], v[86:89], v[198:201], v[22:25]
	v_mfma_f32_16x16x32_bf16 v[18:21], v[94:97], v[198:201], v[18:21]
	v_mfma_f32_16x16x32_bf16 v[6:9], v[86:89], v[206:209], v[6:9]
	v_mfma_f32_16x16x32_bf16 v[2:5], v[94:97], v[206:209], v[2:5]
	s_barrier
	s_add_u32 s6, s6, 0x100
	s_addc_u32 s7, s7, 0
	s_add_u32 s21, s21, 0x100
	s_addc_u32 s26, s26, 0
	s_cmp_ge_u32 s46, s36
	s_mov_b32 s27, s46
	s_cbranch_scc0 .LBB0_671
	s_and_b64 vcc, exec, s[30:31]
	s_cbranch_vccz .LBB0_674
	s_barrier

.LBB0_787:
	s_add_i32 m0, s20, 0xc000
	ds_read_b128 v[56:59], v68 offset:0
	ds_read_b128 v[60:63], v68 offset:1024
	ds_read_b128 v[64:67], v68 offset:2048
	ds_read_b128 v[74:77], v68 offset:3072
	global_load_lds_dwordx4 v38, s[40:41]
	s_add_i32 m0, s20, 0xe000
	ds_read_b128 v[116:119], v55 offset:0
	ds_read_b128 v[120:123], v55 offset:1024
	ds_read_b128 v[124:127], v55 offset:2048
	global_load_lds_dwordx4 v34, s[40:41]
	s_add_i32 m0, s20, 0x21c00
	ds_read_b128 v[128:131], v55 offset:3072
	ds_read_b128 v[132:135], v55 offset:4096
	ds_read_b128 v[136:139], v55 offset:5120
	global_load_lds_dwordx4 v38, s[42:43]
	s_add_i32 m0, s20, 0x23c00
	ds_read_b128 v[140:143], v55 offset:6144
	ds_read_b128 v[144:147], v55 offset:7168
	global_load_lds_dwordx4 v34, s[42:43]
	s_add_i32 m0, s20, 0x4000
	ds_read_b128 v[98:101], v68 offset:16384
	ds_read_b128 v[102:105], v68 offset:17408
	global_load_lds_dwordx4 v40, s[10:11]
	s_add_i32 m0, s20, 0x6000
	ds_read_b128 v[106:109], v68 offset:18432
	ds_read_b128 v[110:113], v68 offset:19456
	global_load_lds_dwordx4 v36, s[10:11]
	s_waitcnt vmcnt(6)
	s_waitcnt lgkmcnt(0)
	s_barrier
	v_mfma_f32_16x16x32_bf16 v[94:97], v[56:59], v[116:119], v[94:97]
	v_mfma_f32_16x16x32_bf16 v[90:93], v[64:67], v[116:119], v[90:93]
	v_mfma_f32_16x16x32_bf16 v[78:81], v[56:59], v[124:127], v[78:81]
	s_add_u32 s40, s4, s8
	v_mfma_f32_16x16x32_bf16 v[70:73], v[64:67], v[124:127], v[70:73]
	s_addc_u32 s41, s5, 0
	v_mfma_f32_16x16x32_bf16 v[30:33], v[56:59], v[132:135], v[30:33]
	s_add_u32 s42, s40, s12
	v_mfma_f32_16x16x32_bf16 v[26:29], v[64:67], v[132:135], v[26:29]
	s_addc_u32 s43, s41, 0
	v_mfma_f32_16x16x32_bf16 v[14:17], v[56:59], v[140:143], v[14:17]
	s_add_u32 s10, s6, s8
	v_mfma_f32_16x16x32_bf16 v[10:13], v[64:67], v[140:143], v[10:13]
	s_addc_u32 s11, s7, 0
	v_mfma_f32_16x16x32_bf16 v[94:97], v[60:63], v[120:123], v[94:97]
	s_addk_i32 s8, 0x80
	v_mfma_f32_16x16x32_bf16 v[90:93], v[74:77], v[120:123], v[90:93]
	s_cmp_eq_u32 s8, s9
	v_mfma_f32_16x16x32_bf16 v[78:81], v[60:63], v[128:131], v[78:81]
	s_cselect_b32 s8, 0, s8
	v_mfma_f32_16x16x32_bf16 v[70:73], v[74:77], v[128:131], v[70:73]
	v_mfma_f32_16x16x32_bf16 v[30:33], v[60:63], v[136:139], v[30:33]
	v_mfma_f32_16x16x32_bf16 v[26:29], v[74:77], v[136:139], v[26:29]
	v_mfma_f32_16x16x32_bf16 v[14:17], v[60:63], v[144:147], v[14:17]
	v_mfma_f32_16x16x32_bf16 v[10:13], v[74:77], v[144:147], v[10:13]
	v_mfma_f32_16x16x32_bf16 v[86:89], v[98:101], v[116:119], v[86:89]
	v_mfma_f32_16x16x32_bf16 v[82:85], v[106:109], v[116:119], v[82:85]
	v_mfma_f32_16x16x32_bf16 v[46:49], v[98:101], v[124:127], v[46:49]
	v_mfma_f32_16x16x32_bf16 v[42:45], v[106:109], v[124:127], v[42:45]
	v_mfma_f32_16x16x32_bf16 v[22:25], v[98:101], v[132:135], v[22:25]
	v_mfma_f32_16x16x32_bf16 v[18:21], v[106:109], v[132:135], v[18:21]
	v_mfma_f32_16x16x32_bf16 v[6:9], v[98:101], v[140:143], v[6:9]
	v_mfma_f32_16x16x32_bf16 v[2:5], v[106:109], v[140:143], v[2:5]
	v_mfma_f32_16x16x32_bf16 v[86:89], v[102:105], v[120:123], v[86:89]
	v_mfma_f32_16x16x32_bf16 v[82:85], v[110:113], v[120:123], v[82:85]
	v_mfma_f32_16x16x32_bf16 v[46:49], v[102:105], v[128:131], v[46:49]
	v_mfma_f32_16x16x32_bf16 v[42:45], v[110:113], v[128:131], v[42:45]
	v_mfma_f32_16x16x32_bf16 v[22:25], v[102:105], v[136:139], v[22:25]
	v_mfma_f32_16x16x32_bf16 v[18:21], v[110:113], v[136:139], v[18:21]
	v_mfma_f32_16x16x32_bf16 v[6:9], v[102:105], v[144:147], v[6:9]
	v_mfma_f32_16x16x32_bf16 v[2:5], v[110:113], v[144:147], v[2:5]
	s_barrier
	s_add_i32 s14, s14, 1
	s_cmp_ge_u32 s14, s36
	s_cbranch_scc1 .Lrt_done
	s_add_i32 m0, s20, 0x10000
	ds_read_b128 v[56:59], v68 offset:32768
	ds_read_b128 v[60:63], v68 offset:33792
	ds_read_b128 v[64:67], v68 offset:34816
	ds_read_b128 v[74:77], v68 offset:35840
	global_load_lds_dwordx4 v38, s[40:41]
	s_add_i32 m0, s20, 0x12000
	ds_read_b128 v[116:119], v55 offset:32768
	ds_read_b128 v[120:123], v55 offset:33792
	ds_read_b128 v[124:127], v55 offset:34816
	global_load_lds_dwordx4 v34, s[40:41]
	s_add_i32 m0, s20, 0x14000
	ds_read_b128 v[128:131], v55 offset:35840
	ds_read_b128 v[132:135], v55 offset:36864
	ds_read_b128 v[136:139], v55 offset:37888
	global_load_lds_dwordx4 v38, s[42:43]
	s_add_i32 m0, s20, 0x16000
	ds_read_b128 v[140:143], v55 offset:38912
	ds_read_b128 v[144:147], v55 offset:39936
	global_load_lds_dwordx4 v34, s[42:43]
	s_add_i32 m0, s20, 0x0
	ds_read_b128 v[98:101], v68 offset:49152
	ds_read_b128 v[102:105], v68 offset:50176
	global_load_lds_dwordx4 v40, s[10:11]
	s_add_i32 m0, s20, 0x2000
	ds_read_b128 v[106:109], v68 offset:51200
	ds_read_b128 v[110:113], v68 offset:52224
	global_load_lds_dwordx4 v36, s[10:11]
	s_waitcnt vmcnt(6)
	s_waitcnt lgkmcnt(0)
	s_barrier
	v_mfma_f32_16x16x32_bf16 v[94:97], v[56:59], v[116:119], v[94:97]
	v_mfma_f32_16x16x32_bf16 v[90:93], v[64:67], v[116:119], v[90:93]
	v_mfma_f32_16x16x32_bf16 v[78:81], v[56:59], v[124:127], v[78:81]
	s_add_u32 s40, s4, s8
	v_mfma_f32_16x16x32_bf16 v[70:73], v[64:67], v[124:127], v[70:73]
	s_addc_u32 s41, s5, 0
	v_mfma_f32_16x16x32_bf16 v[30:33], v[56:59], v[132:135], v[30:33]
	s_add_u32 s42, s40, s12
	v_mfma_f32_16x16x32_bf16 v[26:29], v[64:67], v[132:135], v[26:29]
	s_addc_u32 s43, s41, 0
	v_mfma_f32_16x16x32_bf16 v[14:17], v[56:59], v[140:143], v[14:17]
	s_add_u32 s10, s6, s8
	v_mfma_f32_16x16x32_bf16 v[10:13], v[64:67], v[140:143], v[10:13]
	s_addc_u32 s11, s7, 0
	v_mfma_f32_16x16x32_bf16 v[94:97], v[60:63], v[120:123], v[94:97]
	s_addk_i32 s8, 0x80
	v_mfma_f32_16x16x32_bf16 v[90:93], v[74:77], v[120:123], v[90:93]
	s_cmp_eq_u32 s8, s9
	v_mfma_f32_16x16x32_bf16 v[78:81], v[60:63], v[128:131], v[78:81]
	s_cselect_b32 s8, 0, s8
	v_mfma_f32_16x16x32_bf16 v[70:73], v[74:77], v[128:131], v[70:73]
	v_mfma_f32_16x16x32_bf16 v[30:33], v[60:63], v[136:139], v[30:33]
	v_mfma_f32_16x16x32_bf16 v[26:29], v[74:77], v[136:139], v[26:29]
	v_mfma_f32_16x16x32_bf16 v[14:17], v[60:63], v[144:147], v[14:17]
	v_mfma_f32_16x16x32_bf16 v[10:13], v[74:77], v[144:147], v[10:13]
	v_mfma_f32_16x16x32_bf16 v[86:89], v[98:101], v[116:119], v[86:89]
	v_mfma_f32_16x16x32_bf16 v[82:85], v[106:109], v[116:119], v[82:85]
	v_mfma_f32_16x16x32_bf16 v[46:49], v[98:101], v[124:127], v[46:49]
	v_mfma_f32_16x16x32_bf16 v[42:45], v[106:109], v[124:127], v[42:45]
	v_mfma_f32_16x16x32_bf16 v[22:25], v[98:101], v[132:135], v[22:25]
	v_mfma_f32_16x16x32_bf16 v[18:21], v[106:109], v[132:135], v[18:21]
	v_mfma_f32_16x16x32_bf16 v[6:9], v[98:101], v[140:143], v[6:9]
	v_mfma_f32_16x16x32_bf16 v[2:5], v[106:109], v[140:143], v[2:5]
	v_mfma_f32_16x16x32_bf16 v[86:89], v[102:105], v[120:123], v[86:89]
	v_mfma_f32_16x16x32_bf16 v[82:85], v[110:113], v[120:123], v[82:85]
	v_mfma_f32_16x16x32_bf16 v[46:49], v[102:105], v[128:131], v[46:49]
	v_mfma_f32_16x16x32_bf16 v[42:45], v[110:113], v[128:131], v[42:45]
	v_mfma_f32_16x16x32_bf16 v[22:25], v[102:105], v[136:139], v[22:25]
	v_mfma_f32_16x16x32_bf16 v[18:21], v[110:113], v[136:139], v[18:21]
	v_mfma_f32_16x16x32_bf16 v[6:9], v[102:105], v[144:147], v[6:9]
	v_mfma_f32_16x16x32_bf16 v[2:5], v[110:113], v[144:147], v[2:5]
	s_barrier
	s_add_i32 s14, s14, 1
	s_cmp_ge_u32 s14, s36
	s_cbranch_scc1 .Lrt_done
	s_add_i32 m0, s20, 0x18000
	ds_read_b128 v[56:59], v54 offset:49152
	ds_read_b128 v[60:63], v54 offset:50176
	ds_read_b128 v[64:67], v54 offset:51200
	ds_read_b128 v[74:77], v54 offset:52224
	global_load_lds_dwordx4 v38, s[40:41]
	s_add_i32 m0, s20, 0x1a000
	ds_read_b128 v[116:119], v55 offset:16384
	ds_read_b128 v[120:123], v55 offset:17408
	ds_read_b128 v[124:127], v55 offset:18432
	global_load_lds_dwordx4 v34, s[40:41]
	s_add_i32 m0, s20, 0x1c000
	ds_read_b128 v[128:131], v55 offset:19456
	ds_read_b128 v[132:135], v55 offset:20480
	ds_read_b128 v[136:139], v55 offset:21504
	global_load_lds_dwordx4 v38, s[42:43]
	s_add_i32 m0, s20, 0x1e000
	ds_read_b128 v[140:143], v55 offset:22528
	ds_read_b128 v[144:147], v55 offset:23552
	global_load_lds_dwordx4 v34, s[42:43]
	s_add_i32 m0, s20, 0x8000
	ds_read_b128 v[98:101], v69 offset:0
	ds_read_b128 v[102:105], v69 offset:1024
	global_load_lds_dwordx4 v40, s[10:11]
	s_add_i32 m0, s20, 0xa000
	ds_read_b128 v[106:109], v69 offset:2048
	ds_read_b128 v[110:113], v69 offset:3072
	global_load_lds_dwordx4 v36, s[10:11]
	s_waitcnt vmcnt(6)
	s_waitcnt lgkmcnt(0)
	s_barrier
	v_mfma_f32_16x16x32_bf16 v[94:97], v[56:59], v[116:119], v[94:97]
	v_mfma_f32_16x16x32_bf16 v[90:93], v[64:67], v[116:119], v[90:93]
	v_mfma_f32_16x16x32_bf16 v[78:81], v[56:59], v[124:127], v[78:81]
	s_add_u32 s40, s4, s8
	v_mfma_f32_16x16x32_bf16 v[70:73], v[64:67], v[124:127], v[70:73]
	s_addc_u32 s41, s5, 0
	v_mfma_f32_16x16x32_bf16 v[30:33], v[56:59], v[132:135], v[30:33]
	s_add_u32 s42, s40, s12
	v_mfma_f32_16x16x32_bf16 v[26:29], v[64:67], v[132:135], v[26:29]
	s_addc_u32 s43, s41, 0
	v_mfma_f32_16x16x32_bf16 v[14:17], v[56:59], v[140:143], v[14:17]
	s_add_u32 s10, s6, s8
	v_mfma_f32_16x16x32_bf16 v[10:13], v[64:67], v[140:143], v[10:13]
	s_addc_u32 s11, s7, 0
	v_mfma_f32_16x16x32_bf16 v[94:97], v[60:63], v[120:123], v[94:97]
	s_addk_i32 s8, 0x80
	v_mfma_f32_16x16x32_bf16 v[90:93], v[74:77], v[120:123], v[90:93]
	s_cmp_eq_u32 s8, s9
	v_mfma_f32_16x16x32_bf16 v[78:81], v[60:63], v[128:131], v[78:81]
	s_cselect_b32 s8, 0, s8
	v_mfma_f32_16x16x32_bf16 v[70:73], v[74:77], v[128:131], v[70:73]
	v_mfma_f32_16x16x32_bf16 v[30:33], v[60:63], v[136:139], v[30:33]
	v_mfma_f32_16x16x32_bf16 v[26:29], v[74:77], v[136:139], v[26:29]
	v_mfma_f32_16x16x32_bf16 v[14:17], v[60:63], v[144:147], v[14:17]
	v_mfma_f32_16x16x32_bf16 v[10:13], v[74:77], v[144:147], v[10:13]
	v_mfma_f32_16x16x32_bf16 v[86:89], v[98:101], v[116:119], v[86:89]
	v_mfma_f32_16x16x32_bf16 v[82:85], v[106:109], v[116:119], v[82:85]
	v_mfma_f32_16x16x32_bf16 v[46:49], v[98:101], v[124:127], v[46:49]
	v_mfma_f32_16x16x32_bf16 v[42:45], v[106:109], v[124:127], v[42:45]
	v_mfma_f32_16x16x32_bf16 v[22:25], v[98:101], v[132:135], v[22:25]
	v_mfma_f32_16x16x32_bf16 v[18:21], v[106:109], v[132:135], v[18:21]
	v_mfma_f32_16x16x32_bf16 v[6:9], v[98:101], v[140:143], v[6:9]
	v_mfma_f32_16x16x32_bf16 v[2:5], v[106:109], v[140:143], v[2:5]
	v_mfma_f32_16x16x32_bf16 v[86:89], v[102:105], v[120:123], v[86:89]
	v_mfma_f32_16x16x32_bf16 v[82:85], v[110:113], v[120:123], v[82:85]
	v_mfma_f32_16x16x32_bf16 v[46:49], v[102:105], v[128:131], v[46:49]
	v_mfma_f32_16x16x32_bf16 v[42:45], v[110:113], v[128:131], v[42:45]
	v_mfma_f32_16x16x32_bf16 v[22:25], v[102:105], v[136:139], v[22:25]
	v_mfma_f32_16x16x32_bf16 v[18:21], v[110:113], v[136:139], v[18:21]
	v_mfma_f32_16x16x32_bf16 v[6:9], v[102:105], v[144:147], v[6:9]
	v_mfma_f32_16x16x32_bf16 v[2:5], v[110:113], v[144:147], v[2:5]
	s_barrier
	s_add_i32 s14, s14, 1
	s_cmp_lt_u32 s14, s36
	s_cbranch_scc1 .LBB0_787
